# GEMM K-loops: per-segment s_setprio toggling removed (16 fewer instructions per K-iteration in six loops)
# speedup vs baseline: 1.0091x; 1.0055x over previous
; #define PG8_STAGE(bufoff, gbase, voff) do { _Pragma("unroll") for (int _i = 0; _i < 2; ++_i) \
;         __builtin_amdgcn_global_load_lds((const unsigned*)((const char*)(gbase) + (voff)[_i]), (LAS unsigned*)(lds + (bufoff) + ldsw + _i * 8192), 16, 0, 0); } while (0)
; #define PG8_LDA(dst, b, h) do { _Pragma("unroll") for (int m = 0; m < 4; ++m) _Pragma("unroll") for (int k = 0; k < 2; ++k) dst[m][k] = *(const LAS bf16x8*)(lds + PG8_SA(b, h) + aoff + m * 2048 + k * 1024); } while (0)
; #define PG8_LDB(dst, b, h) do { _Pragma("unroll") for (int n = 0; n < 2; ++n) _Pragma("unroll") for (int k = 0; k < 2; ++k) dst[n][k] = *(const LAS bf16x8*)(lds + PG8_SB(b, h) + boff + n * 2048 + k * 1024); } while (0)
; #define PG8_MMA(ai, bj, At, Bt) do { __builtin_amdgcn_s_setprio(1); _Pragma("unroll") for (int m = 0; m < 4; ++m) _Pragma("unroll") for (int n = 0; n < 2; ++n) _Pragma("unroll") for (int k = 0; k < 2; ++k) \
;         acc[ai][bj][m][n] = __builtin_amdgcn_mfma_f32_16x16x32_bf16(Bt[n][k], At[m][k], acc[ai][bj][m][n], 0, 0, 0); __builtin_amdgcn_s_setprio(0); } while (0)
; #define PG8_WAIT_V(n) asm volatile("s_waitcnt vmcnt(" #n ")" ::: "memory")
; #define PG8_WAIT_L(n) asm volatile("s_waitcnt lgkmcnt(" #n ")" ::: "memory")
; #define PG8_BAR __builtin_amdgcn_s_barrier()
; #define PG8_SCHED __builtin_amdgcn_sched_barrier(0)
; template <class Epi>
; __device__ __forceinline__ void gemm_phase(LAS unsigned char* lds, const Gemm g, const StaticOrder& S, const Epi& E, const int wid) {
;     ...
;             PG8_LDB(B0, 0, 0); PG8_LDB(B1, 0, 1); PG8_SCHED; PG8_LDA(At, 0, 0); PG8_STAGE(PG8_SA(1, 1), a1 + hstepA, voffA);
;             PG8_WAIT_V(8); PG8_WAIT_L(0); PG8_BAR; PG8_MMA(0, 0, At, B0); PG8_MMA(0, 1, At, B1); PG8_BAR; PG8_SCHED;
;             PG8_LDA(At, 0, 1); PG8_STAGE(PG8_SB(0, 0), b2, voffB); PG8_STAGE(PG8_SB(0, 1), b2 + hstepB, voffB); PG8_STAGE(PG8_SA(0, 0), a2, voffA);
;             PG8_WAIT_V(8); PG8_WAIT_L(0); PG8_BAR; PG8_MMA(1, 0, At, B0); PG8_MMA(1, 1, At, B1); PG8_BAR; PG8_SCHED;
;             PG8_LDB(B0, 1, 0); PG8_LDB(B1, 1, 1); PG8_SCHED; PG8_LDA(At, 1, 0); PG8_STAGE(PG8_SA(0, 1), a2 + hstepA, voffA);
;             PG8_WAIT_V(8); PG8_WAIT_L(0); PG8_BAR; PG8_MMA(0, 0, At, B0); PG8_MMA(0, 1, At, B1); PG8_BAR; PG8_SCHED;
.LBB0_157:
	ds_read_b128 v[150:153], v157
	ds_read_b128 v[160:163], v157 offset:1024
	ds_read_b128 v[164:167], v157 offset:2048
	ds_read_b128 v[168:171], v157 offset:3072
	ds_read_b128 v[172:175], v158
	ds_read_b128 v[176:179], v158 offset:1024
	ds_read_b128 v[180:183], v158 offset:2048
	ds_read_b128 v[184:187], v158 offset:3072
	s_add_u32 s8, s10, 0x100
	s_addc_u32 s9, s11, 0
	s_cmp_eq_u32 s60, 28
	s_cselect_b32 s59, s51, s9
	s_cselect_b32 s58, s50, s8
	s_cselect_b32 s57, s20, s55
	s_cselect_b32 s56, s21, s49
	s_add_i32 m0, s0, 0xc000
	ds_read_b128 v[188:191], v159
	global_load_lds_dwordx4 v142, s[10:11]
	s_add_i32 m0, s0, 0xe000
	ds_read_b128 v[192:195], v159 offset:1024
	global_load_lds_dwordx4 v144, s[10:11]
	ds_read_b128 v[196:199], v159 offset:2048
	ds_read_b128 v[200:203], v159 offset:3072
	ds_read_b128 v[204:207], v159 offset:4096
	ds_read_b128 v[208:211], v159 offset:5120
	ds_read_b128 v[212:215], v159 offset:6144
	ds_read_b128 v[216:219], v159 offset:7168
	s_waitcnt vmcnt(8)
	s_waitcnt lgkmcnt(0)
	s_barrier
	s_waitcnt lgkmcnt(0)
	v_mfma_f32_16x16x32_bf16 v[124:127], v[150:153], v[188:191], v[124:127]
	v_mfma_f32_16x16x32_bf16 v[120:123], v[164:167], v[188:191], v[120:123]
	v_mfma_f32_16x16x32_bf16 v[116:119], v[150:153], v[196:199], v[116:119]
	v_mfma_f32_16x16x32_bf16 v[112:115], v[164:167], v[196:199], v[112:115]
	v_mfma_f32_16x16x32_bf16 v[108:111], v[150:153], v[204:207], v[108:111]
	v_mfma_f32_16x16x32_bf16 v[104:107], v[164:167], v[204:207], v[104:107]
	v_mfma_f32_16x16x32_bf16 v[100:103], v[150:153], v[212:215], v[100:103]
	v_mfma_f32_16x16x32_bf16 v[96:99], v[164:167], v[212:215], v[96:99]
	v_mfma_f32_16x16x32_bf16 v[124:127], v[160:163], v[192:195], v[124:127]
	v_mfma_f32_16x16x32_bf16 v[120:123], v[168:171], v[192:195], v[120:123]
	v_mfma_f32_16x16x32_bf16 v[116:119], v[160:163], v[200:203], v[116:119]
	v_mfma_f32_16x16x32_bf16 v[112:115], v[168:171], v[200:203], v[112:115]
	v_mfma_f32_16x16x32_bf16 v[108:111], v[160:163], v[208:211], v[108:111]
	v_mfma_f32_16x16x32_bf16 v[104:107], v[168:171], v[208:211], v[104:107]
	v_mfma_f32_16x16x32_bf16 v[100:103], v[160:163], v[216:219], v[100:103]
	v_mfma_f32_16x16x32_bf16 v[96:99], v[168:171], v[216:219], v[96:99]
	v_mfma_f32_16x16x32_bf16 v[60:63], v[172:175], v[188:191], v[60:63]
	v_mfma_f32_16x16x32_bf16 v[56:59], v[180:183], v[188:191], v[56:59]
	v_mfma_f32_16x16x32_bf16 v[52:55], v[172:175], v[196:199], v[52:55]
	v_mfma_f32_16x16x32_bf16 v[48:51], v[180:183], v[196:199], v[48:51]
	v_mfma_f32_16x16x32_bf16 v[44:47], v[172:175], v[204:207], v[44:47]
	v_mfma_f32_16x16x32_bf16 v[40:43], v[180:183], v[204:207], v[40:43]
	v_mfma_f32_16x16x32_bf16 v[36:39], v[172:175], v[212:215], v[36:39]
	v_mfma_f32_16x16x32_bf16 v[32:35], v[180:183], v[212:215], v[32:35]
	v_mfma_f32_16x16x32_bf16 v[60:63], v[176:179], v[192:195], v[60:63]
	v_mfma_f32_16x16x32_bf16 v[56:59], v[184:187], v[192:195], v[56:59]
	v_mfma_f32_16x16x32_bf16 v[52:55], v[176:179], v[200:203], v[52:55]
	v_mfma_f32_16x16x32_bf16 v[48:51], v[184:187], v[200:203], v[48:51]
	v_mfma_f32_16x16x32_bf16 v[44:47], v[176:179], v[208:211], v[44:47]
	v_mfma_f32_16x16x32_bf16 v[40:43], v[184:187], v[208:211], v[40:43]
	v_mfma_f32_16x16x32_bf16 v[36:39], v[176:179], v[216:219], v[36:39]
	v_mfma_f32_16x16x32_bf16 v[32:35], v[184:187], v[216:219], v[32:35]
	s_barrier
	s_add_i32 s10, s68, s94
	s_mov_b32 m0, s10
	ds_read_b128 v[188:191], v159 offset:16384
	global_load_lds_dwordx4 v130, s[56:57]
	s_add_i32 m0, s10, 0x2000
	s_add_u32 s10, s56, 0x80000
	s_addc_u32 s11, s57, 0
	s_add_i32 s24, s69, s94
	global_load_lds_dwordx4 v134, s[56:57]
	s_mov_b32 m0, s24
	ds_read_b128 v[192:195], v159 offset:17408
	global_load_lds_dwordx4 v130, s[10:11]
	s_add_i32 m0, s24, 0x2000
	ds_read_b128 v[196:199], v159 offset:18432
	global_load_lds_dwordx4 v134, s[10:11]
	s_mov_b32 m0, s0
	ds_read_b128 v[200:203], v159 offset:19456
	global_load_lds_dwordx4 v128, s[58:59]
	s_mov_b32 m0, s1
	ds_read_b128 v[204:207], v159 offset:20480
	global_load_lds_dwordx4 v132, s[58:59]
	ds_read_b128 v[208:211], v159 offset:21504
	ds_read_b128 v[212:215], v159 offset:22528
	ds_read_b128 v[216:219], v159 offset:23552
	s_waitcnt vmcnt(8)
	s_waitcnt lgkmcnt(0)
	s_barrier
	s_waitcnt lgkmcnt(0)
	v_mfma_f32_16x16x32_bf16 v[92:95], v[150:153], v[188:191], v[92:95]
	v_mfma_f32_16x16x32_bf16 v[88:91], v[164:167], v[188:191], v[88:91]
	v_mfma_f32_16x16x32_bf16 v[84:87], v[150:153], v[196:199], v[84:87]
	v_mfma_f32_16x16x32_bf16 v[80:83], v[164:167], v[196:199], v[80:83]
	v_mfma_f32_16x16x32_bf16 v[76:79], v[150:153], v[204:207], v[76:79]
	v_mfma_f32_16x16x32_bf16 v[72:75], v[164:167], v[204:207], v[72:75]
	v_mfma_f32_16x16x32_bf16 v[68:71], v[150:153], v[212:215], v[68:71]
	v_mfma_f32_16x16x32_bf16 v[64:67], v[164:167], v[212:215], v[64:67]
	v_mfma_f32_16x16x32_bf16 v[92:95], v[160:163], v[192:195], v[92:95]
	v_mfma_f32_16x16x32_bf16 v[88:91], v[168:171], v[192:195], v[88:91]
	v_mfma_f32_16x16x32_bf16 v[84:87], v[160:163], v[200:203], v[84:87]
	v_mfma_f32_16x16x32_bf16 v[80:83], v[168:171], v[200:203], v[80:83]
	v_mfma_f32_16x16x32_bf16 v[76:79], v[160:163], v[208:211], v[76:79]
	v_mfma_f32_16x16x32_bf16 v[72:75], v[168:171], v[208:211], v[72:75]
	v_mfma_f32_16x16x32_bf16 v[68:71], v[160:163], v[216:219], v[68:71]
	v_mfma_f32_16x16x32_bf16 v[64:67], v[168:171], v[216:219], v[64:67]
	v_mfma_f32_16x16x32_bf16 v[28:31], v[172:175], v[188:191], v[28:31]
	v_mfma_f32_16x16x32_bf16 v[24:27], v[180:183], v[188:191], v[24:27]
	v_mfma_f32_16x16x32_bf16 v[20:23], v[172:175], v[196:199], v[20:23]
	v_mfma_f32_16x16x32_bf16 v[16:19], v[180:183], v[196:199], v[16:19]
	v_mfma_f32_16x16x32_bf16 v[12:15], v[172:175], v[204:207], v[12:15]
	v_mfma_f32_16x16x32_bf16 v[8:11], v[180:183], v[204:207], v[8:11]
	v_mfma_f32_16x16x32_bf16 v[4:7], v[172:175], v[212:215], v[4:7]
	v_mfma_f32_16x16x32_bf16 v[0:3], v[180:183], v[212:215], v[0:3]
	v_mfma_f32_16x16x32_bf16 v[28:31], v[176:179], v[192:195], v[28:31]
	v_mfma_f32_16x16x32_bf16 v[24:27], v[184:187], v[192:195], v[24:27]
	v_mfma_f32_16x16x32_bf16 v[20:23], v[176:179], v[200:203], v[20:23]
	v_mfma_f32_16x16x32_bf16 v[16:19], v[184:187], v[200:203], v[16:19]
	v_mfma_f32_16x16x32_bf16 v[12:15], v[176:179], v[208:211], v[12:15]
	v_mfma_f32_16x16x32_bf16 v[8:11], v[184:187], v[208:211], v[8:11]
	v_mfma_f32_16x16x32_bf16 v[4:7], v[176:179], v[216:219], v[4:7]
	v_mfma_f32_16x16x32_bf16 v[0:3], v[184:187], v[216:219], v[0:3]
	s_barrier
; #define PG8_STAGE(bufoff, gbase, voff) do { _Pragma("unroll") for (int _i = 0; _i < 2; ++_i) \
;         __builtin_amdgcn_global_load_lds((const unsigned*)((const char*)(gbase) + (voff)[_i]), (LAS unsigned*)(lds + (bufoff) + ldsw + _i * 8192), 16, 0, 0); } while (0)
; #define PG8_LDA(dst, b, h) do { _Pragma("unroll") for (int m = 0; m < 4; ++m) _Pragma("unroll") for (int k = 0; k < 2; ++k) dst[m][k] = *(const LAS bf16x8*)(lds + PG8_SA(b, h) + aoff + m * 2048 + k * 1024); } while (0)
; #define PG8_LDB(dst, b, h) do { _Pragma("unroll") for (int n = 0; n < 2; ++n) _Pragma("unroll") for (int k = 0; k < 2; ++k) dst[n][k] = *(const LAS bf16x8*)(lds + PG8_SB(b, h) + boff + n * 2048 + k * 1024); } while (0)
; #define PG8_MMA(ai, bj, At, Bt) do { __builtin_amdgcn_s_setprio(1); _Pragma("unroll") for (int m = 0; m < 4; ++m) _Pragma("unroll") for (int n = 0; n < 2; ++n) _Pragma("unroll") for (int k = 0; k < 2; ++k) \
;         acc[ai][bj][m][n] = __builtin_amdgcn_mfma_f32_16x16x32_bf16(Bt[n][k], At[m][k], acc[ai][bj][m][n], 0, 0, 0); __builtin_amdgcn_s_setprio(0); } while (0)
; #define PG8_WAIT_V(n) asm volatile("s_waitcnt vmcnt(" #n ")" ::: "memory")
; #define PG8_WAIT_L(n) asm volatile("s_waitcnt lgkmcnt(" #n ")" ::: "memory")
; #define PG8_BAR __builtin_amdgcn_s_barrier()
; #define PG8_SCHED __builtin_amdgcn_sched_barrier(0)
; template <class Epi>
; __device__ __forceinline__ void gemm_phase(LAS unsigned char* lds, const Gemm g, const StaticOrder& S, const Epi& E, const int wid) {
;     ...
;             PG8_LDB(B0, 1, 0); PG8_LDB(B1, 1, 1); PG8_SCHED; PG8_LDA(At, 1, 0); PG8_STAGE(PG8_SA(0, 1), a2 + hstepA, voffA);
;             PG8_WAIT_V(8); PG8_WAIT_L(0); PG8_BAR; PG8_MMA(0, 0, At, B0); PG8_MMA(0, 1, At, B1); PG8_BAR; PG8_SCHED;
;             PG8_LDA(At, 1, 1); PG8_STAGE(PG8_SB(1, 0), b3, voffB); PG8_STAGE(PG8_SB(1, 1), b3 + hstepB, voffB); PG8_STAGE(PG8_SA(1, 0), a3, voffA);
;             PG8_WAIT_V(8); PG8_WAIT_L(0); PG8_BAR; PG8_MMA(1, 0, At, B0); PG8_MMA(1, 1, At, B1); PG8_BAR; PG8_SCHED;
;         }
;         if (wr == 0) PG8_BAR;
	s_add_i32 s24, 0, 0x18000
	v_add_u32_e32 v136, s24, v139
	s_add_i32 s25, 0, 0x1c000
	ds_read_b128 v[150:153], v136
	ds_read_b128 v[160:163], v136 offset:1024
	ds_read_b128 v[164:167], v136 offset:2048
	ds_read_b128 v[168:171], v136 offset:3072
	v_add_u32_e32 v136, s25, v139
	ds_read_b128 v[172:175], v136
	ds_read_b128 v[176:179], v136 offset:1024
	ds_read_b128 v[180:183], v136 offset:2048
	ds_read_b128 v[184:187], v136 offset:3072
	s_add_u32 s10, s58, 0x80000
	s_addc_u32 s11, s59, 0
	s_mov_b32 m0, s15
	ds_read_b128 v[188:191], v159 offset:32768
	global_load_lds_dwordx4 v128, s[10:11]
	s_mov_b32 m0, s26
	ds_read_b128 v[192:195], v159 offset:33792
	global_load_lds_dwordx4 v132, s[10:11]
	ds_read_b128 v[196:199], v159 offset:34816
	ds_read_b128 v[200:203], v159 offset:35840
	ds_read_b128 v[204:207], v159 offset:36864
	ds_read_b128 v[208:211], v159 offset:37888
	ds_read_b128 v[212:215], v159 offset:38912
	ds_read_b128 v[216:219], v159 offset:39936
	s_waitcnt vmcnt(8)
	s_waitcnt lgkmcnt(0)
	s_barrier
	s_waitcnt lgkmcnt(0)
	v_mfma_f32_16x16x32_bf16 v[124:127], v[150:153], v[188:191], v[124:127]
	v_mfma_f32_16x16x32_bf16 v[120:123], v[164:167], v[188:191], v[120:123]
	v_mfma_f32_16x16x32_bf16 v[116:119], v[150:153], v[196:199], v[116:119]
	v_mfma_f32_16x16x32_bf16 v[112:115], v[164:167], v[196:199], v[112:115]
	v_mfma_f32_16x16x32_bf16 v[108:111], v[150:153], v[204:207], v[108:111]
	v_mfma_f32_16x16x32_bf16 v[104:107], v[164:167], v[204:207], v[104:107]
	v_mfma_f32_16x16x32_bf16 v[100:103], v[150:153], v[212:215], v[100:103]
	v_mfma_f32_16x16x32_bf16 v[96:99], v[164:167], v[212:215], v[96:99]
	v_mfma_f32_16x16x32_bf16 v[124:127], v[160:163], v[192:195], v[124:127]
	v_mfma_f32_16x16x32_bf16 v[120:123], v[168:171], v[192:195], v[120:123]
	v_mfma_f32_16x16x32_bf16 v[116:119], v[160:163], v[200:203], v[116:119]
	v_mfma_f32_16x16x32_bf16 v[112:115], v[168:171], v[200:203], v[112:115]
	v_mfma_f32_16x16x32_bf16 v[108:111], v[160:163], v[208:211], v[108:111]
	v_mfma_f32_16x16x32_bf16 v[104:107], v[168:171], v[208:211], v[104:107]
	v_mfma_f32_16x16x32_bf16 v[100:103], v[160:163], v[216:219], v[100:103]
	v_mfma_f32_16x16x32_bf16 v[96:99], v[168:171], v[216:219], v[96:99]
	v_mfma_f32_16x16x32_bf16 v[60:63], v[172:175], v[188:191], v[60:63]
	v_mfma_f32_16x16x32_bf16 v[56:59], v[180:183], v[188:191], v[56:59]
	v_mfma_f32_16x16x32_bf16 v[52:55], v[172:175], v[196:199], v[52:55]
	v_mfma_f32_16x16x32_bf16 v[48:51], v[180:183], v[196:199], v[48:51]
	v_mfma_f32_16x16x32_bf16 v[44:47], v[172:175], v[204:207], v[44:47]
	v_mfma_f32_16x16x32_bf16 v[40:43], v[180:183], v[204:207], v[40:43]
	v_mfma_f32_16x16x32_bf16 v[36:39], v[172:175], v[212:215], v[36:39]
	v_mfma_f32_16x16x32_bf16 v[32:35], v[180:183], v[212:215], v[32:35]
	v_mfma_f32_16x16x32_bf16 v[60:63], v[176:179], v[192:195], v[60:63]
	v_mfma_f32_16x16x32_bf16 v[56:59], v[184:187], v[192:195], v[56:59]
	v_mfma_f32_16x16x32_bf16 v[52:55], v[176:179], v[200:203], v[52:55]
	v_mfma_f32_16x16x32_bf16 v[48:51], v[184:187], v[200:203], v[48:51]
	v_mfma_f32_16x16x32_bf16 v[44:47], v[176:179], v[208:211], v[44:47]
	v_mfma_f32_16x16x32_bf16 v[40:43], v[184:187], v[208:211], v[40:43]
	v_mfma_f32_16x16x32_bf16 v[36:39], v[176:179], v[216:219], v[36:39]
	v_mfma_f32_16x16x32_bf16 v[32:35], v[184:187], v[216:219], v[32:35]
	s_barrier
	s_add_i32 s10, s24, s94
	s_add_u32 s98, s56, 0x80
	s_addc_u32 s99, s57, 0
	s_mov_b32 m0, s10
	ds_read_b128 v[188:191], v159 offset:49152
	global_load_lds_dwordx4 v130, s[98:99]
	s_add_i32 m0, s10, 0x2000
	s_add_u32 s10, s56, 0x80080
	s_addc_u32 s11, s57, 0
	s_add_i32 s24, s25, s94
	global_load_lds_dwordx4 v134, s[98:99]
	s_mov_b32 m0, s24
	ds_read_b128 v[192:195], v159 offset:50176
	global_load_lds_dwordx4 v130, s[10:11]
	s_add_i32 m0, s24, 0x2000
	ds_read_b128 v[196:199], v159 offset:51200
	global_load_lds_dwordx4 v134, s[10:11]
	s_add_u32 s100, s58, 0x80
	s_addc_u32 s101, s59, 0
	s_mov_b32 m0, s66
	ds_read_b128 v[200:203], v159 offset:52224
	global_load_lds_dwordx4 v128, s[100:101]
	s_mov_b32 m0, s67
	ds_read_b128 v[204:207], v159 offset:53248
	global_load_lds_dwordx4 v132, s[100:101]
	ds_read_b128 v[208:211], v159 offset:54272
	ds_read_b128 v[212:215], v159 offset:55296
	ds_read_b128 v[216:219], v159 offset:56320
	s_waitcnt vmcnt(8)
	s_waitcnt lgkmcnt(0)
	s_barrier
	s_waitcnt lgkmcnt(0)
	v_mfma_f32_16x16x32_bf16 v[92:95], v[150:153], v[188:191], v[92:95]
	v_mfma_f32_16x16x32_bf16 v[88:91], v[164:167], v[188:191], v[88:91]
	v_mfma_f32_16x16x32_bf16 v[84:87], v[150:153], v[196:199], v[84:87]
	v_mfma_f32_16x16x32_bf16 v[80:83], v[164:167], v[196:199], v[80:83]
	v_mfma_f32_16x16x32_bf16 v[76:79], v[150:153], v[204:207], v[76:79]
	v_mfma_f32_16x16x32_bf16 v[72:75], v[164:167], v[204:207], v[72:75]
	v_mfma_f32_16x16x32_bf16 v[68:71], v[150:153], v[212:215], v[68:71]
	v_mfma_f32_16x16x32_bf16 v[64:67], v[164:167], v[212:215], v[64:67]
	v_mfma_f32_16x16x32_bf16 v[92:95], v[160:163], v[192:195], v[92:95]
	v_mfma_f32_16x16x32_bf16 v[88:91], v[168:171], v[192:195], v[88:91]
	v_mfma_f32_16x16x32_bf16 v[84:87], v[160:163], v[200:203], v[84:87]
	v_mfma_f32_16x16x32_bf16 v[80:83], v[168:171], v[200:203], v[80:83]
	v_mfma_f32_16x16x32_bf16 v[76:79], v[160:163], v[208:211], v[76:79]
	v_mfma_f32_16x16x32_bf16 v[72:75], v[168:171], v[208:211], v[72:75]
	v_mfma_f32_16x16x32_bf16 v[68:71], v[160:163], v[216:219], v[68:71]
	v_mfma_f32_16x16x32_bf16 v[64:67], v[168:171], v[216:219], v[64:67]
	v_mfma_f32_16x16x32_bf16 v[28:31], v[172:175], v[188:191], v[28:31]
	v_mfma_f32_16x16x32_bf16 v[24:27], v[180:183], v[188:191], v[24:27]
	v_mfma_f32_16x16x32_bf16 v[20:23], v[172:175], v[196:199], v[20:23]
	v_mfma_f32_16x16x32_bf16 v[16:19], v[180:183], v[196:199], v[16:19]
	v_mfma_f32_16x16x32_bf16 v[12:15], v[172:175], v[204:207], v[12:15]
	v_mfma_f32_16x16x32_bf16 v[8:11], v[180:183], v[204:207], v[8:11]
	v_mfma_f32_16x16x32_bf16 v[4:7], v[172:175], v[212:215], v[4:7]
	v_mfma_f32_16x16x32_bf16 v[0:3], v[180:183], v[212:215], v[0:3]
	v_mfma_f32_16x16x32_bf16 v[28:31], v[176:179], v[192:195], v[28:31]
	v_mfma_f32_16x16x32_bf16 v[24:27], v[184:187], v[192:195], v[24:27]
	v_mfma_f32_16x16x32_bf16 v[20:23], v[176:179], v[200:203], v[20:23]
	v_mfma_f32_16x16x32_bf16 v[16:19], v[184:187], v[200:203], v[16:19]
	v_mfma_f32_16x16x32_bf16 v[12:15], v[176:179], v[208:211], v[12:15]
	v_mfma_f32_16x16x32_bf16 v[8:11], v[184:187], v[208:211], v[8:11]
	v_mfma_f32_16x16x32_bf16 v[4:7], v[176:179], v[216:219], v[4:7]
	v_mfma_f32_16x16x32_bf16 v[0:3], v[184:187], v[216:219], v[0:3]
	s_barrier
	s_add_i32 s60, s60, 2
	s_add_u32 s49, s49, 0x100
	s_addc_u32 s55, s55, 0
	s_cmp_gt_u32 s60, 29
	s_mov_b64 s[10:11], s[8:9]
	s_cbranch_scc0 .LBB0_157
	s_and_b64 vcc, exec, s[22:23]
	s_cbranch_vccz .LBB0_160
	s_barrier

; #define PG8_STAGE(bufoff, gbase, voff) do { _Pragma("unroll") for (int _i = 0; _i < 2; ++_i) \
;         __builtin_amdgcn_global_load_lds((const unsigned*)((const char*)(gbase) + (voff)[_i]), (LAS unsigned*)(lds + (bufoff) + ldsw + _i * 8192), 16, 0, 0); } while (0)
; #define PG8_LDA(dst, b, h) do { _Pragma("unroll") for (int m = 0; m < 4; ++m) _Pragma("unroll") for (int k = 0; k < 2; ++k) dst[m][k] = *(const LAS bf16x8*)(lds + PG8_SA(b, h) + aoff + m * 2048 + k * 1024); } while (0)
; #define PG8_LDB(dst, b, h) do { _Pragma("unroll") for (int n = 0; n < 2; ++n) _Pragma("unroll") for (int k = 0; k < 2; ++k) dst[n][k] = *(const LAS bf16x8*)(lds + PG8_SB(b, h) + boff + n * 2048 + k * 1024); } while (0)
; #define PG8_MMA(ai, bj, At, Bt) do { __builtin_amdgcn_s_setprio(1); _Pragma("unroll") for (int m = 0; m < 4; ++m) _Pragma("unroll") for (int n = 0; n < 2; ++n) _Pragma("unroll") for (int k = 0; k < 2; ++k) \
;         acc[ai][bj][m][n] = __builtin_amdgcn_mfma_f32_16x16x32_bf16(Bt[n][k], At[m][k], acc[ai][bj][m][n], 0, 0, 0); __builtin_amdgcn_s_setprio(0); } while (0)
; #define PG8_WAIT_V(n) asm volatile("s_waitcnt vmcnt(" #n ")" ::: "memory")
; #define PG8_WAIT_L(n) asm volatile("s_waitcnt lgkmcnt(" #n ")" ::: "memory")
; #define PG8_BAR __builtin_amdgcn_s_barrier()
; #define PG8_SCHED __builtin_amdgcn_sched_barrier(0)
; template <class Epi>
; __device__ __forceinline__ void gemm_phase(LAS unsigned char* lds, const Gemm g, const StaticOrder& S, const Epi& E, const int wid) {
;     ...
;             const bool last = (t == nt - 2);
;             const char* a1 = cA + (size_t)(t + 1) * kstep;
;             const char* a2 = last ? nA : cA + (size_t)(t + 2) * kstep; const char* b2 = last ? nB : cB + (size_t)(t + 2) * kstep;
;             const char* a3 = a2 + kstep; const char* b3 = b2 + kstep;
;             PG8_LDB(B0, 0, 0); PG8_LDB(B1, 0, 1); PG8_SCHED; PG8_LDA(At, 0, 0); PG8_STAGE(PG8_SA(1, 1), a1 + hstepA, voffA);
;             PG8_WAIT_V(8); PG8_WAIT_L(0); PG8_BAR; PG8_MMA(0, 0, At, B0); PG8_MMA(0, 1, At, B1); PG8_BAR; PG8_SCHED;
;             PG8_LDA(At, 0, 1); PG8_STAGE(PG8_SB(0, 0), b2, voffB); PG8_STAGE(PG8_SB(0, 1), b2 + hstepB, voffB); PG8_STAGE(PG8_SA(0, 0), a2, voffA);
;             PG8_WAIT_V(8); PG8_WAIT_L(0); PG8_BAR; PG8_MMA(1, 0, At, B0); PG8_MMA(1, 1, At, B1); PG8_BAR; PG8_SCHED;
.LBB0_1669:
	ds_read_b128 v[144:147], v157
	ds_read_b128 v[148:151], v157 offset:1024
	ds_read_b128 v[160:163], v157 offset:2048
	ds_read_b128 v[164:167], v157 offset:3072
	ds_read_b128 v[168:171], v158
	ds_read_b128 v[172:175], v158 offset:1024
	ds_read_b128 v[176:179], v158 offset:2048
	ds_read_b128 v[180:183], v158 offset:3072
	s_add_u32 s6, s46, 0x100
	s_addc_u32 s7, s47, 0
	s_cmp_eq_u32 s55, 12
	s_cselect_b32 s51, s43, s7
	s_cselect_b32 s50, s42, s6
	s_cselect_b32 s49, s11, s54
	s_cselect_b32 s48, s21, s53
	s_add_i32 m0, s0, 0xc000
	ds_read_b128 v[184:187], v159
	global_load_lds_dwordx4 v136, s[46:47]
	s_add_i32 m0, s0, 0xe000
	ds_read_b128 v[188:191], v159 offset:1024
	global_load_lds_dwordx4 v138, s[46:47]
	ds_read_b128 v[192:195], v159 offset:2048
	ds_read_b128 v[196:199], v159 offset:3072
	ds_read_b128 v[200:203], v159 offset:4096
	ds_read_b128 v[204:207], v159 offset:5120
	ds_read_b128 v[208:211], v159 offset:6144
	ds_read_b128 v[212:215], v159 offset:7168
	s_waitcnt vmcnt(8)
	s_waitcnt lgkmcnt(0)
	s_barrier
	s_waitcnt lgkmcnt(0)
	v_mfma_f32_16x16x32_bf16 v[124:127], v[144:147], v[184:187], v[124:127]
	v_mfma_f32_16x16x32_bf16 v[120:123], v[160:163], v[184:187], v[120:123]
	v_mfma_f32_16x16x32_bf16 v[116:119], v[144:147], v[192:195], v[116:119]
	v_mfma_f32_16x16x32_bf16 v[112:115], v[160:163], v[192:195], v[112:115]
	v_mfma_f32_16x16x32_bf16 v[108:111], v[144:147], v[200:203], v[108:111]
	v_mfma_f32_16x16x32_bf16 v[104:107], v[160:163], v[200:203], v[104:107]
	v_mfma_f32_16x16x32_bf16 v[100:103], v[144:147], v[208:211], v[100:103]
	v_mfma_f32_16x16x32_bf16 v[96:99], v[160:163], v[208:211], v[96:99]
	v_mfma_f32_16x16x32_bf16 v[124:127], v[148:151], v[188:191], v[124:127]
	v_mfma_f32_16x16x32_bf16 v[120:123], v[164:167], v[188:191], v[120:123]
	v_mfma_f32_16x16x32_bf16 v[116:119], v[148:151], v[196:199], v[116:119]
	v_mfma_f32_16x16x32_bf16 v[112:115], v[164:167], v[196:199], v[112:115]
	v_mfma_f32_16x16x32_bf16 v[108:111], v[148:151], v[204:207], v[108:111]
	v_mfma_f32_16x16x32_bf16 v[104:107], v[164:167], v[204:207], v[104:107]
	v_mfma_f32_16x16x32_bf16 v[100:103], v[148:151], v[212:215], v[100:103]
	v_mfma_f32_16x16x32_bf16 v[96:99], v[164:167], v[212:215], v[96:99]
	v_mfma_f32_16x16x32_bf16 v[68:71], v[168:171], v[184:187], v[68:71]
	v_mfma_f32_16x16x32_bf16 v[60:63], v[176:179], v[184:187], v[60:63]
	v_mfma_f32_16x16x32_bf16 v[52:55], v[168:171], v[192:195], v[52:55]
	v_mfma_f32_16x16x32_bf16 v[48:51], v[176:179], v[192:195], v[48:51]
	v_mfma_f32_16x16x32_bf16 v[44:47], v[168:171], v[200:203], v[44:47]
	v_mfma_f32_16x16x32_bf16 v[40:43], v[176:179], v[200:203], v[40:43]
	v_mfma_f32_16x16x32_bf16 v[36:39], v[168:171], v[208:211], v[36:39]
	v_mfma_f32_16x16x32_bf16 v[32:35], v[176:179], v[208:211], v[32:35]
	v_mfma_f32_16x16x32_bf16 v[68:71], v[172:175], v[188:191], v[68:71]
	v_mfma_f32_16x16x32_bf16 v[60:63], v[180:183], v[188:191], v[60:63]
	v_mfma_f32_16x16x32_bf16 v[52:55], v[172:175], v[196:199], v[52:55]
	v_mfma_f32_16x16x32_bf16 v[48:51], v[180:183], v[196:199], v[48:51]
	v_mfma_f32_16x16x32_bf16 v[44:47], v[172:175], v[204:207], v[44:47]
	v_mfma_f32_16x16x32_bf16 v[40:43], v[180:183], v[204:207], v[40:43]
	v_mfma_f32_16x16x32_bf16 v[36:39], v[172:175], v[212:215], v[36:39]
	v_mfma_f32_16x16x32_bf16 v[32:35], v[180:183], v[212:215], v[32:35]
	s_barrier
	s_add_i32 s24, s36, s94
	s_mov_b32 m0, s24
	ds_read_b128 v[184:187], v159 offset:16384
	global_load_lds_dwordx4 v132, s[48:49]
	s_add_i32 m0, s24, 0x2000
	s_add_u32 s24, s48, 0x40000
	s_addc_u32 s25, s49, 0
	s_add_i32 s46, s37, s94
	global_load_lds_dwordx4 v128, s[48:49]
	s_mov_b32 m0, s46
	ds_read_b128 v[188:191], v159 offset:17408
	global_load_lds_dwordx4 v132, s[24:25]
	s_add_i32 m0, s46, 0x2000
	ds_read_b128 v[192:195], v159 offset:18432
	global_load_lds_dwordx4 v128, s[24:25]
	s_mov_b32 m0, s0
	ds_read_b128 v[196:199], v159 offset:19456
	global_load_lds_dwordx4 v134, s[50:51]
	s_mov_b32 m0, s1
	ds_read_b128 v[200:203], v159 offset:20480
	global_load_lds_dwordx4 v130, s[50:51]
	ds_read_b128 v[204:207], v159 offset:21504
	ds_read_b128 v[208:211], v159 offset:22528
	ds_read_b128 v[212:215], v159 offset:23552
	s_waitcnt vmcnt(8)
	s_waitcnt lgkmcnt(0)
	s_barrier
	s_waitcnt lgkmcnt(0)
	v_mfma_f32_16x16x32_bf16 v[92:95], v[144:147], v[184:187], v[92:95]
	v_mfma_f32_16x16x32_bf16 v[88:91], v[160:163], v[184:187], v[88:91]
	v_mfma_f32_16x16x32_bf16 v[84:87], v[144:147], v[192:195], v[84:87]
	v_mfma_f32_16x16x32_bf16 v[80:83], v[160:163], v[192:195], v[80:83]
	v_mfma_f32_16x16x32_bf16 v[76:79], v[144:147], v[200:203], v[76:79]
	v_mfma_f32_16x16x32_bf16 v[72:75], v[160:163], v[200:203], v[72:75]
	v_mfma_f32_16x16x32_bf16 v[64:67], v[144:147], v[208:211], v[64:67]
	v_mfma_f32_16x16x32_bf16 v[56:59], v[160:163], v[208:211], v[56:59]
	v_mfma_f32_16x16x32_bf16 v[92:95], v[148:151], v[188:191], v[92:95]
	v_mfma_f32_16x16x32_bf16 v[88:91], v[164:167], v[188:191], v[88:91]
	v_mfma_f32_16x16x32_bf16 v[84:87], v[148:151], v[196:199], v[84:87]
	v_mfma_f32_16x16x32_bf16 v[80:83], v[164:167], v[196:199], v[80:83]
	v_mfma_f32_16x16x32_bf16 v[76:79], v[148:151], v[204:207], v[76:79]
	v_mfma_f32_16x16x32_bf16 v[72:75], v[164:167], v[204:207], v[72:75]
	v_mfma_f32_16x16x32_bf16 v[64:67], v[148:151], v[212:215], v[64:67]
	v_mfma_f32_16x16x32_bf16 v[56:59], v[164:167], v[212:215], v[56:59]
	v_mfma_f32_16x16x32_bf16 v[28:31], v[168:171], v[184:187], v[28:31]
	v_mfma_f32_16x16x32_bf16 v[24:27], v[176:179], v[184:187], v[24:27]
	v_mfma_f32_16x16x32_bf16 v[20:23], v[168:171], v[192:195], v[20:23]
	v_mfma_f32_16x16x32_bf16 v[16:19], v[176:179], v[192:195], v[16:19]
	v_mfma_f32_16x16x32_bf16 v[12:15], v[168:171], v[200:203], v[12:15]
	v_mfma_f32_16x16x32_bf16 v[8:11], v[176:179], v[200:203], v[8:11]
	v_mfma_f32_16x16x32_bf16 v[4:7], v[168:171], v[208:211], v[4:7]
	v_mfma_f32_16x16x32_bf16 v[0:3], v[176:179], v[208:211], v[0:3]
	v_mfma_f32_16x16x32_bf16 v[28:31], v[172:175], v[188:191], v[28:31]
	v_mfma_f32_16x16x32_bf16 v[24:27], v[180:183], v[188:191], v[24:27]
	v_mfma_f32_16x16x32_bf16 v[20:23], v[172:175], v[196:199], v[20:23]
	v_mfma_f32_16x16x32_bf16 v[16:19], v[180:183], v[196:199], v[16:19]
	v_mfma_f32_16x16x32_bf16 v[12:15], v[172:175], v[204:207], v[12:15]
	v_mfma_f32_16x16x32_bf16 v[8:11], v[180:183], v[204:207], v[8:11]
	v_mfma_f32_16x16x32_bf16 v[4:7], v[172:175], v[212:215], v[4:7]
	v_mfma_f32_16x16x32_bf16 v[0:3], v[180:183], v[212:215], v[0:3]
	s_barrier
; #define PG8_STAGE(bufoff, gbase, voff) do { _Pragma("unroll") for (int _i = 0; _i < 2; ++_i) \
;         __builtin_amdgcn_global_load_lds((const unsigned*)((const char*)(gbase) + (voff)[_i]), (LAS unsigned*)(lds + (bufoff) + ldsw + _i * 8192), 16, 0, 0); } while (0)
; #define PG8_LDA(dst, b, h) do { _Pragma("unroll") for (int m = 0; m < 4; ++m) _Pragma("unroll") for (int k = 0; k < 2; ++k) dst[m][k] = *(const LAS bf16x8*)(lds + PG8_SA(b, h) + aoff + m * 2048 + k * 1024); } while (0)
; #define PG8_LDB(dst, b, h) do { _Pragma("unroll") for (int n = 0; n < 2; ++n) _Pragma("unroll") for (int k = 0; k < 2; ++k) dst[n][k] = *(const LAS bf16x8*)(lds + PG8_SB(b, h) + boff + n * 2048 + k * 1024); } while (0)
; #define PG8_MMA(ai, bj, At, Bt) do { __builtin_amdgcn_s_setprio(1); _Pragma("unroll") for (int m = 0; m < 4; ++m) _Pragma("unroll") for (int n = 0; n < 2; ++n) _Pragma("unroll") for (int k = 0; k < 2; ++k) \
;         acc[ai][bj][m][n] = __builtin_amdgcn_mfma_f32_16x16x32_bf16(Bt[n][k], At[m][k], acc[ai][bj][m][n], 0, 0, 0); __builtin_amdgcn_s_setprio(0); } while (0)
; #define PG8_WAIT_V(n) asm volatile("s_waitcnt vmcnt(" #n ")" ::: "memory")
; #define PG8_WAIT_L(n) asm volatile("s_waitcnt lgkmcnt(" #n ")" ::: "memory")
; #define PG8_BAR __builtin_amdgcn_s_barrier()
; #define PG8_SCHED __builtin_amdgcn_sched_barrier(0)
; template <class Epi>
; __device__ __forceinline__ void gemm_phase(LAS unsigned char* lds, const Gemm g, const StaticOrder& S, const Epi& E, const int wid) {
;     ...
;             PG8_LDB(B0, 1, 0); PG8_LDB(B1, 1, 1); PG8_SCHED; PG8_LDA(At, 1, 0); PG8_STAGE(PG8_SA(0, 1), a2 + hstepA, voffA);
;             PG8_WAIT_V(8); PG8_WAIT_L(0); PG8_BAR; PG8_MMA(0, 0, At, B0); PG8_MMA(0, 1, At, B1); PG8_BAR; PG8_SCHED;
;             PG8_LDA(At, 1, 1); PG8_STAGE(PG8_SB(1, 0), b3, voffB); PG8_STAGE(PG8_SB(1, 1), b3 + hstepB, voffB); PG8_STAGE(PG8_SA(1, 0), a3, voffA);
;             PG8_WAIT_V(8); PG8_WAIT_L(0); PG8_BAR; PG8_MMA(1, 0, At, B0); PG8_MMA(1, 1, At, B1); PG8_BAR; PG8_SCHED;
;         }
;         if (wr == 0) PG8_BAR;
	s_add_i32 s46, 0, 0x18000
	s_add_i32 s47, 0, 0x1c000
	v_add_u32_e32 v164, s46, v154
	v_add_u32_e32 v180, s47, v154
	ds_read_b128 v[144:147], v164
	ds_read_b128 v[148:151], v164 offset:1024
	ds_read_b128 v[160:163], v164 offset:2048
	ds_read_b128 v[164:167], v164 offset:3072
	ds_read_b128 v[168:171], v180
	ds_read_b128 v[172:175], v180 offset:1024
	ds_read_b128 v[176:179], v180 offset:2048
	ds_read_b128 v[180:183], v180 offset:3072
	s_add_u32 s24, s50, 0x40000
	s_addc_u32 s25, s51, 0
	s_mov_b32 m0, s15
	ds_read_b128 v[184:187], v159 offset:32768
	global_load_lds_dwordx4 v134, s[24:25]
	s_mov_b32 m0, s26
	ds_read_b128 v[188:191], v159 offset:33792
	global_load_lds_dwordx4 v130, s[24:25]
	ds_read_b128 v[192:195], v159 offset:34816
	ds_read_b128 v[196:199], v159 offset:35840
	ds_read_b128 v[200:203], v159 offset:36864
	ds_read_b128 v[204:207], v159 offset:37888
	ds_read_b128 v[208:211], v159 offset:38912
	ds_read_b128 v[212:215], v159 offset:39936
	s_waitcnt vmcnt(8)
	s_waitcnt lgkmcnt(0)
	s_barrier
	s_waitcnt lgkmcnt(0)
	v_mfma_f32_16x16x32_bf16 v[124:127], v[144:147], v[184:187], v[124:127]
	v_mfma_f32_16x16x32_bf16 v[120:123], v[160:163], v[184:187], v[120:123]
	v_mfma_f32_16x16x32_bf16 v[116:119], v[144:147], v[192:195], v[116:119]
	v_mfma_f32_16x16x32_bf16 v[112:115], v[160:163], v[192:195], v[112:115]
	v_mfma_f32_16x16x32_bf16 v[108:111], v[144:147], v[200:203], v[108:111]
	v_mfma_f32_16x16x32_bf16 v[104:107], v[160:163], v[200:203], v[104:107]
	v_mfma_f32_16x16x32_bf16 v[100:103], v[144:147], v[208:211], v[100:103]
	v_mfma_f32_16x16x32_bf16 v[96:99], v[160:163], v[208:211], v[96:99]
	v_mfma_f32_16x16x32_bf16 v[124:127], v[148:151], v[188:191], v[124:127]
	v_mfma_f32_16x16x32_bf16 v[120:123], v[164:167], v[188:191], v[120:123]
	v_mfma_f32_16x16x32_bf16 v[116:119], v[148:151], v[196:199], v[116:119]
	v_mfma_f32_16x16x32_bf16 v[112:115], v[164:167], v[196:199], v[112:115]
	v_mfma_f32_16x16x32_bf16 v[108:111], v[148:151], v[204:207], v[108:111]
	v_mfma_f32_16x16x32_bf16 v[104:107], v[164:167], v[204:207], v[104:107]
	v_mfma_f32_16x16x32_bf16 v[100:103], v[148:151], v[212:215], v[100:103]
	v_mfma_f32_16x16x32_bf16 v[96:99], v[164:167], v[212:215], v[96:99]
	v_mfma_f32_16x16x32_bf16 v[68:71], v[168:171], v[184:187], v[68:71]
	v_mfma_f32_16x16x32_bf16 v[60:63], v[176:179], v[184:187], v[60:63]
	v_mfma_f32_16x16x32_bf16 v[52:55], v[168:171], v[192:195], v[52:55]
	v_mfma_f32_16x16x32_bf16 v[48:51], v[176:179], v[192:195], v[48:51]
	v_mfma_f32_16x16x32_bf16 v[44:47], v[168:171], v[200:203], v[44:47]
	v_mfma_f32_16x16x32_bf16 v[40:43], v[176:179], v[200:203], v[40:43]
	v_mfma_f32_16x16x32_bf16 v[36:39], v[168:171], v[208:211], v[36:39]
	v_mfma_f32_16x16x32_bf16 v[32:35], v[176:179], v[208:211], v[32:35]
	v_mfma_f32_16x16x32_bf16 v[68:71], v[172:175], v[188:191], v[68:71]
	v_mfma_f32_16x16x32_bf16 v[60:63], v[180:183], v[188:191], v[60:63]
	v_mfma_f32_16x16x32_bf16 v[52:55], v[172:175], v[196:199], v[52:55]
	v_mfma_f32_16x16x32_bf16 v[48:51], v[180:183], v[196:199], v[48:51]
	v_mfma_f32_16x16x32_bf16 v[44:47], v[172:175], v[204:207], v[44:47]
	v_mfma_f32_16x16x32_bf16 v[40:43], v[180:183], v[204:207], v[40:43]
	v_mfma_f32_16x16x32_bf16 v[36:39], v[172:175], v[212:215], v[36:39]
	v_mfma_f32_16x16x32_bf16 v[32:35], v[180:183], v[212:215], v[32:35]
	s_barrier
	s_add_i32 s24, s46, s94
	s_add_u32 s98, s48, 0x80
	s_addc_u32 s99, s49, 0
	s_mov_b32 m0, s24
	ds_read_b128 v[184:187], v159 offset:49152
	global_load_lds_dwordx4 v132, s[98:99]
	s_add_i32 m0, s24, 0x2000
	s_add_u32 s24, s48, 0x40080
	s_addc_u32 s25, s49, 0
	s_add_i32 s46, s47, s94
	global_load_lds_dwordx4 v128, s[98:99]
	s_mov_b32 m0, s46
	ds_read_b128 v[188:191], v159 offset:50176
	global_load_lds_dwordx4 v132, s[24:25]
	s_add_i32 m0, s46, 0x2000
	ds_read_b128 v[192:195], v159 offset:51200
	global_load_lds_dwordx4 v128, s[24:25]
	s_add_u32 s100, s50, 0x80
	s_addc_u32 s101, s51, 0
	s_mov_b32 m0, s28
	ds_read_b128 v[196:199], v159 offset:52224
	global_load_lds_dwordx4 v134, s[100:101]
	s_mov_b32 m0, s29
	ds_read_b128 v[200:203], v159 offset:53248
	global_load_lds_dwordx4 v130, s[100:101]
	ds_read_b128 v[204:207], v159 offset:54272
	ds_read_b128 v[208:211], v159 offset:55296
	ds_read_b128 v[212:215], v159 offset:56320
	s_waitcnt vmcnt(8)
	s_waitcnt lgkmcnt(0)
	s_barrier
	s_waitcnt lgkmcnt(0)
	v_mfma_f32_16x16x32_bf16 v[92:95], v[144:147], v[184:187], v[92:95]
	v_mfma_f32_16x16x32_bf16 v[88:91], v[160:163], v[184:187], v[88:91]
	v_mfma_f32_16x16x32_bf16 v[84:87], v[144:147], v[192:195], v[84:87]
	v_mfma_f32_16x16x32_bf16 v[80:83], v[160:163], v[192:195], v[80:83]
	v_mfma_f32_16x16x32_bf16 v[76:79], v[144:147], v[200:203], v[76:79]
	v_mfma_f32_16x16x32_bf16 v[72:75], v[160:163], v[200:203], v[72:75]
	v_mfma_f32_16x16x32_bf16 v[64:67], v[144:147], v[208:211], v[64:67]
	v_mfma_f32_16x16x32_bf16 v[56:59], v[160:163], v[208:211], v[56:59]
	v_mfma_f32_16x16x32_bf16 v[92:95], v[148:151], v[188:191], v[92:95]
	v_mfma_f32_16x16x32_bf16 v[88:91], v[164:167], v[188:191], v[88:91]
	v_mfma_f32_16x16x32_bf16 v[84:87], v[148:151], v[196:199], v[84:87]
	v_mfma_f32_16x16x32_bf16 v[80:83], v[164:167], v[196:199], v[80:83]
	v_mfma_f32_16x16x32_bf16 v[76:79], v[148:151], v[204:207], v[76:79]
	v_mfma_f32_16x16x32_bf16 v[72:75], v[164:167], v[204:207], v[72:75]
	v_mfma_f32_16x16x32_bf16 v[64:67], v[148:151], v[212:215], v[64:67]
	v_mfma_f32_16x16x32_bf16 v[56:59], v[164:167], v[212:215], v[56:59]
	v_mfma_f32_16x16x32_bf16 v[28:31], v[168:171], v[184:187], v[28:31]
	v_mfma_f32_16x16x32_bf16 v[24:27], v[176:179], v[184:187], v[24:27]
	v_mfma_f32_16x16x32_bf16 v[20:23], v[168:171], v[192:195], v[20:23]
	v_mfma_f32_16x16x32_bf16 v[16:19], v[176:179], v[192:195], v[16:19]
	v_mfma_f32_16x16x32_bf16 v[12:15], v[168:171], v[200:203], v[12:15]
	v_mfma_f32_16x16x32_bf16 v[8:11], v[176:179], v[200:203], v[8:11]
	v_mfma_f32_16x16x32_bf16 v[4:7], v[168:171], v[208:211], v[4:7]
	v_mfma_f32_16x16x32_bf16 v[0:3], v[176:179], v[208:211], v[0:3]
	v_mfma_f32_16x16x32_bf16 v[28:31], v[172:175], v[188:191], v[28:31]
	v_mfma_f32_16x16x32_bf16 v[24:27], v[180:183], v[188:191], v[24:27]
	v_mfma_f32_16x16x32_bf16 v[20:23], v[172:175], v[196:199], v[20:23]
	v_mfma_f32_16x16x32_bf16 v[16:19], v[180:183], v[196:199], v[16:19]
	v_mfma_f32_16x16x32_bf16 v[12:15], v[172:175], v[204:207], v[12:15]
	v_mfma_f32_16x16x32_bf16 v[8:11], v[180:183], v[204:207], v[8:11]
	v_mfma_f32_16x16x32_bf16 v[4:7], v[172:175], v[212:215], v[4:7]
	v_mfma_f32_16x16x32_bf16 v[0:3], v[180:183], v[212:215], v[0:3]
	s_barrier
	s_add_i32 s55, s55, 2
	s_add_u32 s53, s53, 0x100
	s_addc_u32 s54, s54, 0
	s_cmp_gt_u32 s55, 13
	s_mov_b64 s[46:47], s[6:7]
	s_cbranch_scc0 .LBB0_1669
	s_and_b64 vcc, exec, s[22:23]
	s_cbranch_vccz .LBB0_1672
	s_barrier

; #define PG8_STAGE(bufoff, gbase, voff) do { _Pragma("unroll") for (int _i = 0; _i < 2; ++_i) \
;         __builtin_amdgcn_global_load_lds((const unsigned*)((const char*)(gbase) + (voff)[_i]), (LAS unsigned*)(lds + (bufoff) + ldsw + _i * 8192), 16, 0, 0); } while (0)
; #define PG8_LDA(dst, b, h) do { _Pragma("unroll") for (int m = 0; m < 4; ++m) _Pragma("unroll") for (int k = 0; k < 2; ++k) dst[m][k] = *(const LAS bf16x8*)(lds + PG8_SA(b, h) + aoff + m * 2048 + k * 1024); } while (0)
; #define PG8_LDB(dst, b, h) do { _Pragma("unroll") for (int n = 0; n < 2; ++n) _Pragma("unroll") for (int k = 0; k < 2; ++k) dst[n][k] = *(const LAS bf16x8*)(lds + PG8_SB(b, h) + boff + n * 2048 + k * 1024); } while (0)
; #define PG8_MMA(ai, bj, At, Bt) do { __builtin_amdgcn_s_setprio(1); _Pragma("unroll") for (int m = 0; m < 4; ++m) _Pragma("unroll") for (int n = 0; n < 2; ++n) _Pragma("unroll") for (int k = 0; k < 2; ++k) \
;         acc[ai][bj][m][n] = __builtin_amdgcn_mfma_f32_16x16x32_bf16(Bt[n][k], At[m][k], acc[ai][bj][m][n], 0, 0, 0); __builtin_amdgcn_s_setprio(0); } while (0)
; #define PG8_WAIT_V(n) asm volatile("s_waitcnt vmcnt(" #n ")" ::: "memory")
; #define PG8_WAIT_L(n) asm volatile("s_waitcnt lgkmcnt(" #n ")" ::: "memory")
; #define PG8_BAR __builtin_amdgcn_s_barrier()
; #define PG8_SCHED __builtin_amdgcn_sched_barrier(0)
; template <class Epi>
; __device__ __forceinline__ void gemm_phase(LAS unsigned char* lds, const Gemm g, const StaticOrder& S, const Epi& E, const int wid) {
;     ...
;             const bool last = (t == nt - 2);
;             const char* a1 = cA + (size_t)(t + 1) * kstep;
;             const char* a2 = last ? nA : cA + (size_t)(t + 2) * kstep; const char* b2 = last ? nB : cB + (size_t)(t + 2) * kstep;
;             const char* a3 = a2 + kstep; const char* b3 = b2 + kstep;
;             PG8_LDB(B0, 0, 0); PG8_LDB(B1, 0, 1); PG8_SCHED; PG8_LDA(At, 0, 0); PG8_STAGE(PG8_SA(1, 1), a1 + hstepA, voffA);
;             PG8_WAIT_V(8); PG8_WAIT_L(0); PG8_BAR; PG8_MMA(0, 0, At, B0); PG8_MMA(0, 1, At, B1); PG8_BAR; PG8_SCHED;
;             PG8_LDA(At, 0, 1); PG8_STAGE(PG8_SB(0, 0), b2, voffB); PG8_STAGE(PG8_SB(0, 1), b2 + hstepB, voffB); PG8_STAGE(PG8_SA(0, 0), a2, voffA);
;             PG8_WAIT_V(8); PG8_WAIT_L(0); PG8_BAR; PG8_MMA(1, 0, At, B0); PG8_MMA(1, 1, At, B1); PG8_BAR; PG8_SCHED;
.LBB0_1692:
	ds_read_b128 v[144:147], v159
	ds_read_b128 v[148:151], v159 offset:1024
	ds_read_b128 v[152:155], v159 offset:2048
	ds_read_b128 v[162:165], v159 offset:3072
	ds_read_b128 v[166:169], v160
	ds_read_b128 v[170:173], v160 offset:1024
	ds_read_b128 v[174:177], v160 offset:2048
	ds_read_b128 v[178:181], v160 offset:3072
	s_add_u32 s6, s50, 0x100
	s_addc_u32 s7, s51, 0
	s_cmp_eq_u32 s58, 12
	s_cselect_b32 s55, s47, s7
	s_cselect_b32 s54, s46, s6
	s_cselect_b32 s53, s21, s57
	s_cselect_b32 s52, s38, s45
	s_add_i32 m0, s0, 0xc000
	ds_read_b128 v[182:185], v161
	global_load_lds_dwordx4 v136, s[50:51]
	s_add_i32 m0, s0, 0xe000
	ds_read_b128 v[186:189], v161 offset:1024
	global_load_lds_dwordx4 v138, s[50:51]
	ds_read_b128 v[190:193], v161 offset:2048
	ds_read_b128 v[194:197], v161 offset:3072
	ds_read_b128 v[198:201], v161 offset:4096
	ds_read_b128 v[202:205], v161 offset:5120
	ds_read_b128 v[206:209], v161 offset:6144
	ds_read_b128 v[210:213], v161 offset:7168
	s_waitcnt vmcnt(8)
	s_waitcnt lgkmcnt(0)
	s_barrier
	s_waitcnt lgkmcnt(0)
	v_mfma_f32_16x16x32_bf16 v[124:127], v[144:147], v[182:185], v[124:127]
	v_mfma_f32_16x16x32_bf16 v[120:123], v[152:155], v[182:185], v[120:123]
	v_mfma_f32_16x16x32_bf16 v[116:119], v[144:147], v[190:193], v[116:119]
	v_mfma_f32_16x16x32_bf16 v[112:115], v[152:155], v[190:193], v[112:115]
	v_mfma_f32_16x16x32_bf16 v[108:111], v[144:147], v[198:201], v[108:111]
	v_mfma_f32_16x16x32_bf16 v[104:107], v[152:155], v[198:201], v[104:107]
	v_mfma_f32_16x16x32_bf16 v[100:103], v[144:147], v[206:209], v[100:103]
	v_mfma_f32_16x16x32_bf16 v[96:99], v[152:155], v[206:209], v[96:99]
	v_mfma_f32_16x16x32_bf16 v[124:127], v[148:151], v[186:189], v[124:127]
	v_mfma_f32_16x16x32_bf16 v[120:123], v[162:165], v[186:189], v[120:123]
	v_mfma_f32_16x16x32_bf16 v[116:119], v[148:151], v[194:197], v[116:119]
	v_mfma_f32_16x16x32_bf16 v[112:115], v[162:165], v[194:197], v[112:115]
	v_mfma_f32_16x16x32_bf16 v[108:111], v[148:151], v[202:205], v[108:111]
	v_mfma_f32_16x16x32_bf16 v[104:107], v[162:165], v[202:205], v[104:107]
	v_mfma_f32_16x16x32_bf16 v[100:103], v[148:151], v[210:213], v[100:103]
	v_mfma_f32_16x16x32_bf16 v[96:99], v[162:165], v[210:213], v[96:99]
	v_mfma_f32_16x16x32_bf16 v[60:63], v[166:169], v[182:185], v[60:63]
	v_mfma_f32_16x16x32_bf16 v[56:59], v[174:177], v[182:185], v[56:59]
	v_mfma_f32_16x16x32_bf16 v[52:55], v[166:169], v[190:193], v[52:55]
	v_mfma_f32_16x16x32_bf16 v[48:51], v[174:177], v[190:193], v[48:51]
	v_mfma_f32_16x16x32_bf16 v[44:47], v[166:169], v[198:201], v[44:47]
	v_mfma_f32_16x16x32_bf16 v[40:43], v[174:177], v[198:201], v[40:43]
	v_mfma_f32_16x16x32_bf16 v[36:39], v[166:169], v[206:209], v[36:39]
	v_mfma_f32_16x16x32_bf16 v[32:35], v[174:177], v[206:209], v[32:35]
	v_mfma_f32_16x16x32_bf16 v[60:63], v[170:173], v[186:189], v[60:63]
	v_mfma_f32_16x16x32_bf16 v[56:59], v[178:181], v[186:189], v[56:59]
	v_mfma_f32_16x16x32_bf16 v[52:55], v[170:173], v[194:197], v[52:55]
	v_mfma_f32_16x16x32_bf16 v[48:51], v[178:181], v[194:197], v[48:51]
	v_mfma_f32_16x16x32_bf16 v[44:47], v[170:173], v[202:205], v[44:47]
	v_mfma_f32_16x16x32_bf16 v[40:43], v[178:181], v[202:205], v[40:43]
	v_mfma_f32_16x16x32_bf16 v[36:39], v[170:173], v[210:213], v[36:39]
	v_mfma_f32_16x16x32_bf16 v[32:35], v[178:181], v[210:213], v[32:35]
	s_barrier
	s_add_i32 s24, s34, s94
	s_mov_b32 m0, s24
	ds_read_b128 v[182:185], v161 offset:16384
	global_load_lds_dwordx4 v132, s[52:53]
	s_add_i32 m0, s24, 0x2000
	s_add_u32 s24, s52, 0x40000
	s_addc_u32 s25, s53, 0
	s_add_i32 s50, s35, s94
	global_load_lds_dwordx4 v128, s[52:53]
	s_mov_b32 m0, s50
	ds_read_b128 v[186:189], v161 offset:17408
	global_load_lds_dwordx4 v132, s[24:25]
	s_add_i32 m0, s50, 0x2000
	ds_read_b128 v[190:193], v161 offset:18432
	global_load_lds_dwordx4 v128, s[24:25]
	s_mov_b32 m0, s0
	ds_read_b128 v[194:197], v161 offset:19456
	global_load_lds_dwordx4 v134, s[54:55]
	s_mov_b32 m0, s1
	ds_read_b128 v[198:201], v161 offset:20480
	global_load_lds_dwordx4 v130, s[54:55]
	ds_read_b128 v[202:205], v161 offset:21504
	ds_read_b128 v[206:209], v161 offset:22528
	ds_read_b128 v[210:213], v161 offset:23552
	s_waitcnt vmcnt(8)
	s_waitcnt lgkmcnt(0)
	s_barrier
	s_waitcnt lgkmcnt(0)
	v_mfma_f32_16x16x32_bf16 v[92:95], v[144:147], v[182:185], v[92:95]
	v_mfma_f32_16x16x32_bf16 v[88:91], v[152:155], v[182:185], v[88:91]
	v_mfma_f32_16x16x32_bf16 v[84:87], v[144:147], v[190:193], v[84:87]
	v_mfma_f32_16x16x32_bf16 v[80:83], v[152:155], v[190:193], v[80:83]
	v_mfma_f32_16x16x32_bf16 v[76:79], v[144:147], v[198:201], v[76:79]
	v_mfma_f32_16x16x32_bf16 v[72:75], v[152:155], v[198:201], v[72:75]
	v_mfma_f32_16x16x32_bf16 v[68:71], v[144:147], v[206:209], v[68:71]
	v_mfma_f32_16x16x32_bf16 v[64:67], v[152:155], v[206:209], v[64:67]
	v_mfma_f32_16x16x32_bf16 v[92:95], v[148:151], v[186:189], v[92:95]
	v_mfma_f32_16x16x32_bf16 v[88:91], v[162:165], v[186:189], v[88:91]
	v_mfma_f32_16x16x32_bf16 v[84:87], v[148:151], v[194:197], v[84:87]
	v_mfma_f32_16x16x32_bf16 v[80:83], v[162:165], v[194:197], v[80:83]
	v_mfma_f32_16x16x32_bf16 v[76:79], v[148:151], v[202:205], v[76:79]
	v_mfma_f32_16x16x32_bf16 v[72:75], v[162:165], v[202:205], v[72:75]
	v_mfma_f32_16x16x32_bf16 v[68:71], v[148:151], v[210:213], v[68:71]
	v_mfma_f32_16x16x32_bf16 v[64:67], v[162:165], v[210:213], v[64:67]
	v_mfma_f32_16x16x32_bf16 v[28:31], v[166:169], v[182:185], v[28:31]
	v_mfma_f32_16x16x32_bf16 v[24:27], v[174:177], v[182:185], v[24:27]
	v_mfma_f32_16x16x32_bf16 v[20:23], v[166:169], v[190:193], v[20:23]
	v_mfma_f32_16x16x32_bf16 v[16:19], v[174:177], v[190:193], v[16:19]
	v_mfma_f32_16x16x32_bf16 v[12:15], v[166:169], v[198:201], v[12:15]
	v_mfma_f32_16x16x32_bf16 v[8:11], v[174:177], v[198:201], v[8:11]
	v_mfma_f32_16x16x32_bf16 v[4:7], v[166:169], v[206:209], v[4:7]
	v_mfma_f32_16x16x32_bf16 v[0:3], v[174:177], v[206:209], v[0:3]
	v_mfma_f32_16x16x32_bf16 v[28:31], v[170:173], v[186:189], v[28:31]
	v_mfma_f32_16x16x32_bf16 v[24:27], v[178:181], v[186:189], v[24:27]
	v_mfma_f32_16x16x32_bf16 v[20:23], v[170:173], v[194:197], v[20:23]
	v_mfma_f32_16x16x32_bf16 v[16:19], v[178:181], v[194:197], v[16:19]
	v_mfma_f32_16x16x32_bf16 v[12:15], v[170:173], v[202:205], v[12:15]
	v_mfma_f32_16x16x32_bf16 v[8:11], v[178:181], v[202:205], v[8:11]
	v_mfma_f32_16x16x32_bf16 v[4:7], v[170:173], v[210:213], v[4:7]
	v_mfma_f32_16x16x32_bf16 v[0:3], v[178:181], v[210:213], v[0:3]
	s_barrier
; #define PG8_STAGE(bufoff, gbase, voff) do { _Pragma("unroll") for (int _i = 0; _i < 2; ++_i) \
;         __builtin_amdgcn_global_load_lds((const unsigned*)((const char*)(gbase) + (voff)[_i]), (LAS unsigned*)(lds + (bufoff) + ldsw + _i * 8192), 16, 0, 0); } while (0)
; #define PG8_LDA(dst, b, h) do { _Pragma("unroll") for (int m = 0; m < 4; ++m) _Pragma("unroll") for (int k = 0; k < 2; ++k) dst[m][k] = *(const LAS bf16x8*)(lds + PG8_SA(b, h) + aoff + m * 2048 + k * 1024); } while (0)
; #define PG8_LDB(dst, b, h) do { _Pragma("unroll") for (int n = 0; n < 2; ++n) _Pragma("unroll") for (int k = 0; k < 2; ++k) dst[n][k] = *(const LAS bf16x8*)(lds + PG8_SB(b, h) + boff + n * 2048 + k * 1024); } while (0)
; #define PG8_MMA(ai, bj, At, Bt) do { __builtin_amdgcn_s_setprio(1); _Pragma("unroll") for (int m = 0; m < 4; ++m) _Pragma("unroll") for (int n = 0; n < 2; ++n) _Pragma("unroll") for (int k = 0; k < 2; ++k) \
;         acc[ai][bj][m][n] = __builtin_amdgcn_mfma_f32_16x16x32_bf16(Bt[n][k], At[m][k], acc[ai][bj][m][n], 0, 0, 0); __builtin_amdgcn_s_setprio(0); } while (0)
; #define PG8_WAIT_V(n) asm volatile("s_waitcnt vmcnt(" #n ")" ::: "memory")
; #define PG8_WAIT_L(n) asm volatile("s_waitcnt lgkmcnt(" #n ")" ::: "memory")
; #define PG8_BAR __builtin_amdgcn_s_barrier()
; #define PG8_SCHED __builtin_amdgcn_sched_barrier(0)
; template <class Epi>
; __device__ __forceinline__ void gemm_phase(LAS unsigned char* lds, const Gemm g, const StaticOrder& S, const Epi& E, const int wid) {
;     ...
;             PG8_LDB(B0, 1, 0); PG8_LDB(B1, 1, 1); PG8_SCHED; PG8_LDA(At, 1, 0); PG8_STAGE(PG8_SA(0, 1), a2 + hstepA, voffA);
;             PG8_WAIT_V(8); PG8_WAIT_L(0); PG8_BAR; PG8_MMA(0, 0, At, B0); PG8_MMA(0, 1, At, B1); PG8_BAR; PG8_SCHED;
;             PG8_LDA(At, 1, 1); PG8_STAGE(PG8_SB(1, 0), b3, voffB); PG8_STAGE(PG8_SB(1, 1), b3 + hstepB, voffB); PG8_STAGE(PG8_SA(1, 0), a3, voffA);
;             PG8_WAIT_V(8); PG8_WAIT_L(0); PG8_BAR; PG8_MMA(1, 0, At, B0); PG8_MMA(1, 1, At, B1); PG8_BAR; PG8_SCHED;
;         }
;         if (wr == 0) PG8_BAR;
	s_add_i32 s50, 0, 0x18000
	s_add_i32 s51, 0, 0x1c000
	v_add_u32_e32 v162, s50, v156
	v_add_u32_e32 v178, s51, v156
	ds_read_b128 v[144:147], v162
	ds_read_b128 v[148:151], v162 offset:1024
	ds_read_b128 v[152:155], v162 offset:2048
	ds_read_b128 v[162:165], v162 offset:3072
	ds_read_b128 v[166:169], v178
	ds_read_b128 v[170:173], v178 offset:1024
	ds_read_b128 v[174:177], v178 offset:2048
	ds_read_b128 v[178:181], v178 offset:3072
	s_add_u32 s24, s54, 0x40000
	s_addc_u32 s25, s55, 0
	s_mov_b32 m0, s15
	ds_read_b128 v[182:185], v161 offset:32768
	global_load_lds_dwordx4 v134, s[24:25]
	s_mov_b32 m0, s26
	ds_read_b128 v[186:189], v161 offset:33792
	global_load_lds_dwordx4 v130, s[24:25]
	ds_read_b128 v[190:193], v161 offset:34816
	ds_read_b128 v[194:197], v161 offset:35840
	ds_read_b128 v[198:201], v161 offset:36864
	ds_read_b128 v[202:205], v161 offset:37888
	ds_read_b128 v[206:209], v161 offset:38912
	ds_read_b128 v[210:213], v161 offset:39936
	s_waitcnt vmcnt(8)
	s_waitcnt lgkmcnt(0)
	s_barrier
	s_waitcnt lgkmcnt(0)
	v_mfma_f32_16x16x32_bf16 v[124:127], v[144:147], v[182:185], v[124:127]
	v_mfma_f32_16x16x32_bf16 v[120:123], v[152:155], v[182:185], v[120:123]
	v_mfma_f32_16x16x32_bf16 v[116:119], v[144:147], v[190:193], v[116:119]
	v_mfma_f32_16x16x32_bf16 v[112:115], v[152:155], v[190:193], v[112:115]
	v_mfma_f32_16x16x32_bf16 v[108:111], v[144:147], v[198:201], v[108:111]
	v_mfma_f32_16x16x32_bf16 v[104:107], v[152:155], v[198:201], v[104:107]
	v_mfma_f32_16x16x32_bf16 v[100:103], v[144:147], v[206:209], v[100:103]
	v_mfma_f32_16x16x32_bf16 v[96:99], v[152:155], v[206:209], v[96:99]
	v_mfma_f32_16x16x32_bf16 v[124:127], v[148:151], v[186:189], v[124:127]
	v_mfma_f32_16x16x32_bf16 v[120:123], v[162:165], v[186:189], v[120:123]
	v_mfma_f32_16x16x32_bf16 v[116:119], v[148:151], v[194:197], v[116:119]
	v_mfma_f32_16x16x32_bf16 v[112:115], v[162:165], v[194:197], v[112:115]
	v_mfma_f32_16x16x32_bf16 v[108:111], v[148:151], v[202:205], v[108:111]
	v_mfma_f32_16x16x32_bf16 v[104:107], v[162:165], v[202:205], v[104:107]
	v_mfma_f32_16x16x32_bf16 v[100:103], v[148:151], v[210:213], v[100:103]
	v_mfma_f32_16x16x32_bf16 v[96:99], v[162:165], v[210:213], v[96:99]
	v_mfma_f32_16x16x32_bf16 v[60:63], v[166:169], v[182:185], v[60:63]
	v_mfma_f32_16x16x32_bf16 v[56:59], v[174:177], v[182:185], v[56:59]
	v_mfma_f32_16x16x32_bf16 v[52:55], v[166:169], v[190:193], v[52:55]
	v_mfma_f32_16x16x32_bf16 v[48:51], v[174:177], v[190:193], v[48:51]
	v_mfma_f32_16x16x32_bf16 v[44:47], v[166:169], v[198:201], v[44:47]
	v_mfma_f32_16x16x32_bf16 v[40:43], v[174:177], v[198:201], v[40:43]
	v_mfma_f32_16x16x32_bf16 v[36:39], v[166:169], v[206:209], v[36:39]
	v_mfma_f32_16x16x32_bf16 v[32:35], v[174:177], v[206:209], v[32:35]
	v_mfma_f32_16x16x32_bf16 v[60:63], v[170:173], v[186:189], v[60:63]
	v_mfma_f32_16x16x32_bf16 v[56:59], v[178:181], v[186:189], v[56:59]
	v_mfma_f32_16x16x32_bf16 v[52:55], v[170:173], v[194:197], v[52:55]
	v_mfma_f32_16x16x32_bf16 v[48:51], v[178:181], v[194:197], v[48:51]
	v_mfma_f32_16x16x32_bf16 v[44:47], v[170:173], v[202:205], v[44:47]
	v_mfma_f32_16x16x32_bf16 v[40:43], v[178:181], v[202:205], v[40:43]
	v_mfma_f32_16x16x32_bf16 v[36:39], v[170:173], v[210:213], v[36:39]
	v_mfma_f32_16x16x32_bf16 v[32:35], v[178:181], v[210:213], v[32:35]
	s_barrier
	s_add_i32 s24, s50, s94
	s_add_u32 s98, s52, 0x80
	s_addc_u32 s99, s53, 0
	s_mov_b32 m0, s24
	ds_read_b128 v[182:185], v161 offset:49152
	global_load_lds_dwordx4 v132, s[98:99]
	s_add_i32 m0, s24, 0x2000
	s_add_u32 s24, s52, 0x40080
	s_addc_u32 s25, s53, 0
	s_add_i32 s50, s51, s94
	global_load_lds_dwordx4 v128, s[98:99]
	s_mov_b32 m0, s50
	ds_read_b128 v[186:189], v161 offset:50176
	global_load_lds_dwordx4 v132, s[24:25]
	s_add_i32 m0, s50, 0x2000
	ds_read_b128 v[190:193], v161 offset:51200
	global_load_lds_dwordx4 v128, s[24:25]
	s_add_u32 s100, s54, 0x80
	s_addc_u32 s101, s55, 0
	s_mov_b32 m0, s28
	ds_read_b128 v[194:197], v161 offset:52224
	global_load_lds_dwordx4 v134, s[100:101]
	s_mov_b32 m0, s29
	ds_read_b128 v[198:201], v161 offset:53248
	global_load_lds_dwordx4 v130, s[100:101]
	ds_read_b128 v[202:205], v161 offset:54272
	ds_read_b128 v[206:209], v161 offset:55296
	ds_read_b128 v[210:213], v161 offset:56320
	s_waitcnt vmcnt(8)
	s_waitcnt lgkmcnt(0)
	s_barrier
	s_waitcnt lgkmcnt(0)
	v_mfma_f32_16x16x32_bf16 v[92:95], v[144:147], v[182:185], v[92:95]
	v_mfma_f32_16x16x32_bf16 v[88:91], v[152:155], v[182:185], v[88:91]
	v_mfma_f32_16x16x32_bf16 v[84:87], v[144:147], v[190:193], v[84:87]
	v_mfma_f32_16x16x32_bf16 v[80:83], v[152:155], v[190:193], v[80:83]
	v_mfma_f32_16x16x32_bf16 v[76:79], v[144:147], v[198:201], v[76:79]
	v_mfma_f32_16x16x32_bf16 v[72:75], v[152:155], v[198:201], v[72:75]
	v_mfma_f32_16x16x32_bf16 v[68:71], v[144:147], v[206:209], v[68:71]
	v_mfma_f32_16x16x32_bf16 v[64:67], v[152:155], v[206:209], v[64:67]
	v_mfma_f32_16x16x32_bf16 v[92:95], v[148:151], v[186:189], v[92:95]
	v_mfma_f32_16x16x32_bf16 v[88:91], v[162:165], v[186:189], v[88:91]
	v_mfma_f32_16x16x32_bf16 v[84:87], v[148:151], v[194:197], v[84:87]
	v_mfma_f32_16x16x32_bf16 v[80:83], v[162:165], v[194:197], v[80:83]
	v_mfma_f32_16x16x32_bf16 v[76:79], v[148:151], v[202:205], v[76:79]
	v_mfma_f32_16x16x32_bf16 v[72:75], v[162:165], v[202:205], v[72:75]
	v_mfma_f32_16x16x32_bf16 v[68:71], v[148:151], v[210:213], v[68:71]
	v_mfma_f32_16x16x32_bf16 v[64:67], v[162:165], v[210:213], v[64:67]
	v_mfma_f32_16x16x32_bf16 v[28:31], v[166:169], v[182:185], v[28:31]
	v_mfma_f32_16x16x32_bf16 v[24:27], v[174:177], v[182:185], v[24:27]
	v_mfma_f32_16x16x32_bf16 v[20:23], v[166:169], v[190:193], v[20:23]
	v_mfma_f32_16x16x32_bf16 v[16:19], v[174:177], v[190:193], v[16:19]
	v_mfma_f32_16x16x32_bf16 v[12:15], v[166:169], v[198:201], v[12:15]
	v_mfma_f32_16x16x32_bf16 v[8:11], v[174:177], v[198:201], v[8:11]
	v_mfma_f32_16x16x32_bf16 v[4:7], v[166:169], v[206:209], v[4:7]
	v_mfma_f32_16x16x32_bf16 v[0:3], v[174:177], v[206:209], v[0:3]
	v_mfma_f32_16x16x32_bf16 v[28:31], v[170:173], v[186:189], v[28:31]
	v_mfma_f32_16x16x32_bf16 v[24:27], v[178:181], v[186:189], v[24:27]
	v_mfma_f32_16x16x32_bf16 v[20:23], v[170:173], v[194:197], v[20:23]
	v_mfma_f32_16x16x32_bf16 v[16:19], v[178:181], v[194:197], v[16:19]
	v_mfma_f32_16x16x32_bf16 v[12:15], v[170:173], v[202:205], v[12:15]
	v_mfma_f32_16x16x32_bf16 v[8:11], v[178:181], v[202:205], v[8:11]
	v_mfma_f32_16x16x32_bf16 v[4:7], v[170:173], v[210:213], v[4:7]
	v_mfma_f32_16x16x32_bf16 v[0:3], v[178:181], v[210:213], v[0:3]
	s_barrier
	s_add_i32 s58, s58, 2
	s_add_u32 s45, s45, 0x100
	s_addc_u32 s57, s57, 0
	s_cmp_gt_u32 s58, 13
	s_mov_b64 s[50:51], s[6:7]
	s_cbranch_scc0 .LBB0_1692
	s_and_b64 vcc, exec, s[22:23]
	s_cbranch_vccz .LBB0_1695
	s_barrier

; #define PG8_STAGE(bufoff, gbase, voff) do { _Pragma("unroll") for (int _i = 0; _i < 2; ++_i) \
;         __builtin_amdgcn_global_load_lds((const unsigned*)((const char*)(gbase) + (voff)[_i]), (LAS unsigned*)(lds + (bufoff) + ldsw + _i * 8192), 16, 0, 0); } while (0)
; #define PG8_LDA(dst, b, h) do { _Pragma("unroll") for (int m = 0; m < 4; ++m) _Pragma("unroll") for (int k = 0; k < 2; ++k) dst[m][k] = *(const LAS bf16x8*)(lds + PG8_SA(b, h) + aoff + m * 2048 + k * 1024); } while (0)
; #define PG8_LDB(dst, b, h) do { _Pragma("unroll") for (int n = 0; n < 2; ++n) _Pragma("unroll") for (int k = 0; k < 2; ++k) dst[n][k] = *(const LAS bf16x8*)(lds + PG8_SB(b, h) + boff + n * 2048 + k * 1024); } while (0)
; #define PG8_MMA(ai, bj, At, Bt) do { __builtin_amdgcn_s_setprio(1); _Pragma("unroll") for (int m = 0; m < 4; ++m) _Pragma("unroll") for (int n = 0; n < 2; ++n) _Pragma("unroll") for (int k = 0; k < 2; ++k) \
;         acc[ai][bj][m][n] = __builtin_amdgcn_mfma_f32_16x16x32_bf16(Bt[n][k], At[m][k], acc[ai][bj][m][n], 0, 0, 0); __builtin_amdgcn_s_setprio(0); } while (0)
; #define PG8_WAIT_V(n) asm volatile("s_waitcnt vmcnt(" #n ")" ::: "memory")
; #define PG8_WAIT_L(n) asm volatile("s_waitcnt lgkmcnt(" #n ")" ::: "memory")
; #define PG8_BAR __builtin_amdgcn_s_barrier()
; #define PG8_SCHED __builtin_amdgcn_sched_barrier(0)
; template <class Epi>
; __device__ __forceinline__ void gemm_phase(LAS unsigned char* lds, const Gemm g, const StaticOrder& S, const Epi& E, const int wid) {
;     ...
;             const bool last = (t == nt - 2);
;             const char* a1 = cA + (size_t)(t + 1) * kstep;
;             const char* a2 = last ? nA : cA + (size_t)(t + 2) * kstep; const char* b2 = last ? nB : cB + (size_t)(t + 2) * kstep;
;             const char* a3 = a2 + kstep; const char* b3 = b2 + kstep;
;             PG8_LDB(B0, 0, 0); PG8_LDB(B1, 0, 1); PG8_SCHED; PG8_LDA(At, 0, 0); PG8_STAGE(PG8_SA(1, 1), a1 + hstepA, voffA);
;             PG8_WAIT_V(8); PG8_WAIT_L(0); PG8_BAR; PG8_MMA(0, 0, At, B0); PG8_MMA(0, 1, At, B1); PG8_BAR; PG8_SCHED;
;             PG8_LDA(At, 0, 1); PG8_STAGE(PG8_SB(0, 0), b2, voffB); PG8_STAGE(PG8_SB(0, 1), b2 + hstepB, voffB); PG8_STAGE(PG8_SA(0, 0), a2, voffA);
;             PG8_WAIT_V(8); PG8_WAIT_L(0); PG8_BAR; PG8_MMA(1, 0, At, B0); PG8_MMA(1, 1, At, B1); PG8_BAR; PG8_SCHED;
.LBB0_1727:
	ds_read_b128 v[144:147], v157
	ds_read_b128 v[148:151], v157 offset:1024
	ds_read_b128 v[160:163], v157 offset:2048
	ds_read_b128 v[164:167], v157 offset:3072
	ds_read_b128 v[168:171], v158
	ds_read_b128 v[172:175], v158 offset:1024
	ds_read_b128 v[176:179], v158 offset:2048
	ds_read_b128 v[180:183], v158 offset:3072
	s_add_u32 s6, s46, 0x100
	s_addc_u32 s7, s47, 0
	s_cmp_eq_u32 s54, 28
	s_cselect_b32 s51, s43, s7
	s_cselect_b32 s50, s42, s6
	s_cselect_b32 s49, s21, s53
	s_cselect_b32 s48, s41, s52
	s_add_i32 m0, s1, 0xc000
	ds_read_b128 v[184:187], v159
	global_load_lds_dwordx4 v136, s[46:47]
	s_add_i32 m0, s1, 0xe000
	ds_read_b128 v[188:191], v159 offset:1024
	global_load_lds_dwordx4 v138, s[46:47]
	ds_read_b128 v[192:195], v159 offset:2048
	ds_read_b128 v[196:199], v159 offset:3072
	ds_read_b128 v[200:203], v159 offset:4096
	ds_read_b128 v[204:207], v159 offset:5120
	ds_read_b128 v[208:211], v159 offset:6144
	ds_read_b128 v[212:215], v159 offset:7168
	s_waitcnt vmcnt(8)
	s_waitcnt lgkmcnt(0)
	s_barrier
	s_waitcnt lgkmcnt(0)
	v_mfma_f32_16x16x32_bf16 v[124:127], v[144:147], v[184:187], v[124:127]
	v_mfma_f32_16x16x32_bf16 v[120:123], v[160:163], v[184:187], v[120:123]
	v_mfma_f32_16x16x32_bf16 v[116:119], v[144:147], v[192:195], v[116:119]
	v_mfma_f32_16x16x32_bf16 v[112:115], v[160:163], v[192:195], v[112:115]
	v_mfma_f32_16x16x32_bf16 v[108:111], v[144:147], v[200:203], v[108:111]
	v_mfma_f32_16x16x32_bf16 v[104:107], v[160:163], v[200:203], v[104:107]
	v_mfma_f32_16x16x32_bf16 v[100:103], v[144:147], v[208:211], v[100:103]
	v_mfma_f32_16x16x32_bf16 v[96:99], v[160:163], v[208:211], v[96:99]
	v_mfma_f32_16x16x32_bf16 v[124:127], v[148:151], v[188:191], v[124:127]
	v_mfma_f32_16x16x32_bf16 v[120:123], v[164:167], v[188:191], v[120:123]
	v_mfma_f32_16x16x32_bf16 v[116:119], v[148:151], v[196:199], v[116:119]
	v_mfma_f32_16x16x32_bf16 v[112:115], v[164:167], v[196:199], v[112:115]
	v_mfma_f32_16x16x32_bf16 v[108:111], v[148:151], v[204:207], v[108:111]
	v_mfma_f32_16x16x32_bf16 v[104:107], v[164:167], v[204:207], v[104:107]
	v_mfma_f32_16x16x32_bf16 v[100:103], v[148:151], v[212:215], v[100:103]
	v_mfma_f32_16x16x32_bf16 v[96:99], v[164:167], v[212:215], v[96:99]
	v_mfma_f32_16x16x32_bf16 v[76:79], v[168:171], v[184:187], v[76:79]
	v_mfma_f32_16x16x32_bf16 v[64:67], v[176:179], v[184:187], v[64:67]
	v_mfma_f32_16x16x32_bf16 v[56:59], v[168:171], v[192:195], v[56:59]
	v_mfma_f32_16x16x32_bf16 v[48:51], v[176:179], v[192:195], v[48:51]
	v_mfma_f32_16x16x32_bf16 v[44:47], v[168:171], v[200:203], v[44:47]
	v_mfma_f32_16x16x32_bf16 v[40:43], v[176:179], v[200:203], v[40:43]
	v_mfma_f32_16x16x32_bf16 v[36:39], v[168:171], v[208:211], v[36:39]
	v_mfma_f32_16x16x32_bf16 v[32:35], v[176:179], v[208:211], v[32:35]
	v_mfma_f32_16x16x32_bf16 v[76:79], v[172:175], v[188:191], v[76:79]
	v_mfma_f32_16x16x32_bf16 v[64:67], v[180:183], v[188:191], v[64:67]
	v_mfma_f32_16x16x32_bf16 v[56:59], v[172:175], v[196:199], v[56:59]
	v_mfma_f32_16x16x32_bf16 v[48:51], v[180:183], v[196:199], v[48:51]
	v_mfma_f32_16x16x32_bf16 v[44:47], v[172:175], v[204:207], v[44:47]
	v_mfma_f32_16x16x32_bf16 v[40:43], v[180:183], v[204:207], v[40:43]
	v_mfma_f32_16x16x32_bf16 v[36:39], v[172:175], v[212:215], v[36:39]
	v_mfma_f32_16x16x32_bf16 v[32:35], v[180:183], v[212:215], v[32:35]
	s_barrier
	s_add_i32 s24, s35, s94
	s_mov_b32 m0, s24
	ds_read_b128 v[184:187], v159 offset:16384
	global_load_lds_dwordx4 v132, s[48:49]
	s_add_i32 m0, s24, 0x2000
	s_add_u32 s24, s48, 0x80000
	s_addc_u32 s25, s49, 0
	s_add_i32 s46, s36, s94
	global_load_lds_dwordx4 v128, s[48:49]
	s_mov_b32 m0, s46
	ds_read_b128 v[188:191], v159 offset:17408
	global_load_lds_dwordx4 v132, s[24:25]
	s_add_i32 m0, s46, 0x2000
	ds_read_b128 v[192:195], v159 offset:18432
	global_load_lds_dwordx4 v128, s[24:25]
	s_mov_b32 m0, s1
	ds_read_b128 v[196:199], v159 offset:19456
	global_load_lds_dwordx4 v134, s[50:51]
	s_mov_b32 m0, s15
	ds_read_b128 v[200:203], v159 offset:20480
	global_load_lds_dwordx4 v130, s[50:51]
	ds_read_b128 v[204:207], v159 offset:21504
	ds_read_b128 v[208:211], v159 offset:22528
	ds_read_b128 v[212:215], v159 offset:23552
	s_waitcnt vmcnt(8)
	s_waitcnt lgkmcnt(0)
	s_barrier
	s_waitcnt lgkmcnt(0)
	v_mfma_f32_16x16x32_bf16 v[92:95], v[144:147], v[184:187], v[92:95]
	v_mfma_f32_16x16x32_bf16 v[88:91], v[160:163], v[184:187], v[88:91]
	v_mfma_f32_16x16x32_bf16 v[84:87], v[144:147], v[192:195], v[84:87]
	v_mfma_f32_16x16x32_bf16 v[80:83], v[160:163], v[192:195], v[80:83]
	v_mfma_f32_16x16x32_bf16 v[72:75], v[144:147], v[200:203], v[72:75]
	v_mfma_f32_16x16x32_bf16 v[68:71], v[160:163], v[200:203], v[68:71]
	v_mfma_f32_16x16x32_bf16 v[60:63], v[144:147], v[208:211], v[60:63]
	v_mfma_f32_16x16x32_bf16 v[52:55], v[160:163], v[208:211], v[52:55]
	v_mfma_f32_16x16x32_bf16 v[92:95], v[148:151], v[188:191], v[92:95]
	v_mfma_f32_16x16x32_bf16 v[88:91], v[164:167], v[188:191], v[88:91]
	v_mfma_f32_16x16x32_bf16 v[84:87], v[148:151], v[196:199], v[84:87]
	v_mfma_f32_16x16x32_bf16 v[80:83], v[164:167], v[196:199], v[80:83]
	v_mfma_f32_16x16x32_bf16 v[72:75], v[148:151], v[204:207], v[72:75]
	v_mfma_f32_16x16x32_bf16 v[68:71], v[164:167], v[204:207], v[68:71]
	v_mfma_f32_16x16x32_bf16 v[60:63], v[148:151], v[212:215], v[60:63]
	v_mfma_f32_16x16x32_bf16 v[52:55], v[164:167], v[212:215], v[52:55]
	v_mfma_f32_16x16x32_bf16 v[28:31], v[168:171], v[184:187], v[28:31]
	v_mfma_f32_16x16x32_bf16 v[24:27], v[176:179], v[184:187], v[24:27]
	v_mfma_f32_16x16x32_bf16 v[20:23], v[168:171], v[192:195], v[20:23]
	v_mfma_f32_16x16x32_bf16 v[16:19], v[176:179], v[192:195], v[16:19]
	v_mfma_f32_16x16x32_bf16 v[12:15], v[168:171], v[200:203], v[12:15]
	v_mfma_f32_16x16x32_bf16 v[8:11], v[176:179], v[200:203], v[8:11]
	v_mfma_f32_16x16x32_bf16 v[4:7], v[168:171], v[208:211], v[4:7]
	v_mfma_f32_16x16x32_bf16 v[0:3], v[176:179], v[208:211], v[0:3]
	v_mfma_f32_16x16x32_bf16 v[28:31], v[172:175], v[188:191], v[28:31]
	v_mfma_f32_16x16x32_bf16 v[24:27], v[180:183], v[188:191], v[24:27]
	v_mfma_f32_16x16x32_bf16 v[20:23], v[172:175], v[196:199], v[20:23]
	v_mfma_f32_16x16x32_bf16 v[16:19], v[180:183], v[196:199], v[16:19]
	v_mfma_f32_16x16x32_bf16 v[12:15], v[172:175], v[204:207], v[12:15]
	v_mfma_f32_16x16x32_bf16 v[8:11], v[180:183], v[204:207], v[8:11]
	v_mfma_f32_16x16x32_bf16 v[4:7], v[172:175], v[212:215], v[4:7]
	v_mfma_f32_16x16x32_bf16 v[0:3], v[180:183], v[212:215], v[0:3]
	s_barrier
; #define PG8_STAGE(bufoff, gbase, voff) do { _Pragma("unroll") for (int _i = 0; _i < 2; ++_i) \
;         __builtin_amdgcn_global_load_lds((const unsigned*)((const char*)(gbase) + (voff)[_i]), (LAS unsigned*)(lds + (bufoff) + ldsw + _i * 8192), 16, 0, 0); } while (0)
; #define PG8_LDA(dst, b, h) do { _Pragma("unroll") for (int m = 0; m < 4; ++m) _Pragma("unroll") for (int k = 0; k < 2; ++k) dst[m][k] = *(const LAS bf16x8*)(lds + PG8_SA(b, h) + aoff + m * 2048 + k * 1024); } while (0)
; #define PG8_LDB(dst, b, h) do { _Pragma("unroll") for (int n = 0; n < 2; ++n) _Pragma("unroll") for (int k = 0; k < 2; ++k) dst[n][k] = *(const LAS bf16x8*)(lds + PG8_SB(b, h) + boff + n * 2048 + k * 1024); } while (0)
; #define PG8_MMA(ai, bj, At, Bt) do { __builtin_amdgcn_s_setprio(1); _Pragma("unroll") for (int m = 0; m < 4; ++m) _Pragma("unroll") for (int n = 0; n < 2; ++n) _Pragma("unroll") for (int k = 0; k < 2; ++k) \
;         acc[ai][bj][m][n] = __builtin_amdgcn_mfma_f32_16x16x32_bf16(Bt[n][k], At[m][k], acc[ai][bj][m][n], 0, 0, 0); __builtin_amdgcn_s_setprio(0); } while (0)
; #define PG8_WAIT_V(n) asm volatile("s_waitcnt vmcnt(" #n ")" ::: "memory")
; #define PG8_WAIT_L(n) asm volatile("s_waitcnt lgkmcnt(" #n ")" ::: "memory")
; #define PG8_BAR __builtin_amdgcn_s_barrier()
; #define PG8_SCHED __builtin_amdgcn_sched_barrier(0)
; template <class Epi>
; __device__ __forceinline__ void gemm_phase(LAS unsigned char* lds, const Gemm g, const StaticOrder& S, const Epi& E, const int wid) {
;     ...
;             PG8_LDB(B0, 1, 0); PG8_LDB(B1, 1, 1); PG8_SCHED; PG8_LDA(At, 1, 0); PG8_STAGE(PG8_SA(0, 1), a2 + hstepA, voffA);
;             PG8_WAIT_V(8); PG8_WAIT_L(0); PG8_BAR; PG8_MMA(0, 0, At, B0); PG8_MMA(0, 1, At, B1); PG8_BAR; PG8_SCHED;
;             PG8_LDA(At, 1, 1); PG8_STAGE(PG8_SB(1, 0), b3, voffB); PG8_STAGE(PG8_SB(1, 1), b3 + hstepB, voffB); PG8_STAGE(PG8_SA(1, 0), a3, voffA);
;             PG8_WAIT_V(8); PG8_WAIT_L(0); PG8_BAR; PG8_MMA(1, 0, At, B0); PG8_MMA(1, 1, At, B1); PG8_BAR; PG8_SCHED;
;         }
;         if (wr == 0) PG8_BAR;
	s_add_i32 s46, 0, 0x18000
	s_add_i32 s47, 0, 0x1c000
	v_add_u32_e32 v164, s46, v154
	v_add_u32_e32 v180, s47, v154
	ds_read_b128 v[144:147], v164
	ds_read_b128 v[148:151], v164 offset:1024
	ds_read_b128 v[160:163], v164 offset:2048
	ds_read_b128 v[164:167], v164 offset:3072
	ds_read_b128 v[168:171], v180
	ds_read_b128 v[172:175], v180 offset:1024
	ds_read_b128 v[176:179], v180 offset:2048
	ds_read_b128 v[180:183], v180 offset:3072
	s_add_u32 s24, s50, 0x80000
	s_addc_u32 s25, s51, 0
	s_mov_b32 m0, s26
	ds_read_b128 v[184:187], v159 offset:32768
	global_load_lds_dwordx4 v134, s[24:25]
	s_mov_b32 m0, s27
	ds_read_b128 v[188:191], v159 offset:33792
	global_load_lds_dwordx4 v130, s[24:25]
	ds_read_b128 v[192:195], v159 offset:34816
	ds_read_b128 v[196:199], v159 offset:35840
	ds_read_b128 v[200:203], v159 offset:36864
	ds_read_b128 v[204:207], v159 offset:37888
	ds_read_b128 v[208:211], v159 offset:38912
	ds_read_b128 v[212:215], v159 offset:39936
	s_waitcnt vmcnt(8)
	s_waitcnt lgkmcnt(0)
	s_barrier
	s_waitcnt lgkmcnt(0)
	v_mfma_f32_16x16x32_bf16 v[124:127], v[144:147], v[184:187], v[124:127]
	v_mfma_f32_16x16x32_bf16 v[120:123], v[160:163], v[184:187], v[120:123]
	v_mfma_f32_16x16x32_bf16 v[116:119], v[144:147], v[192:195], v[116:119]
	v_mfma_f32_16x16x32_bf16 v[112:115], v[160:163], v[192:195], v[112:115]
	v_mfma_f32_16x16x32_bf16 v[108:111], v[144:147], v[200:203], v[108:111]
	v_mfma_f32_16x16x32_bf16 v[104:107], v[160:163], v[200:203], v[104:107]
	v_mfma_f32_16x16x32_bf16 v[100:103], v[144:147], v[208:211], v[100:103]
	v_mfma_f32_16x16x32_bf16 v[96:99], v[160:163], v[208:211], v[96:99]
	v_mfma_f32_16x16x32_bf16 v[124:127], v[148:151], v[188:191], v[124:127]
	v_mfma_f32_16x16x32_bf16 v[120:123], v[164:167], v[188:191], v[120:123]
	v_mfma_f32_16x16x32_bf16 v[116:119], v[148:151], v[196:199], v[116:119]
	v_mfma_f32_16x16x32_bf16 v[112:115], v[164:167], v[196:199], v[112:115]
	v_mfma_f32_16x16x32_bf16 v[108:111], v[148:151], v[204:207], v[108:111]
	v_mfma_f32_16x16x32_bf16 v[104:107], v[164:167], v[204:207], v[104:107]
	v_mfma_f32_16x16x32_bf16 v[100:103], v[148:151], v[212:215], v[100:103]
	v_mfma_f32_16x16x32_bf16 v[96:99], v[164:167], v[212:215], v[96:99]
	v_mfma_f32_16x16x32_bf16 v[76:79], v[168:171], v[184:187], v[76:79]
	v_mfma_f32_16x16x32_bf16 v[64:67], v[176:179], v[184:187], v[64:67]
	v_mfma_f32_16x16x32_bf16 v[56:59], v[168:171], v[192:195], v[56:59]
	v_mfma_f32_16x16x32_bf16 v[48:51], v[176:179], v[192:195], v[48:51]
	v_mfma_f32_16x16x32_bf16 v[44:47], v[168:171], v[200:203], v[44:47]
	v_mfma_f32_16x16x32_bf16 v[40:43], v[176:179], v[200:203], v[40:43]
	v_mfma_f32_16x16x32_bf16 v[36:39], v[168:171], v[208:211], v[36:39]
	v_mfma_f32_16x16x32_bf16 v[32:35], v[176:179], v[208:211], v[32:35]
	v_mfma_f32_16x16x32_bf16 v[76:79], v[172:175], v[188:191], v[76:79]
	v_mfma_f32_16x16x32_bf16 v[64:67], v[180:183], v[188:191], v[64:67]
	v_mfma_f32_16x16x32_bf16 v[56:59], v[172:175], v[196:199], v[56:59]
	v_mfma_f32_16x16x32_bf16 v[48:51], v[180:183], v[196:199], v[48:51]
	v_mfma_f32_16x16x32_bf16 v[44:47], v[172:175], v[204:207], v[44:47]
	v_mfma_f32_16x16x32_bf16 v[40:43], v[180:183], v[204:207], v[40:43]
	v_mfma_f32_16x16x32_bf16 v[36:39], v[172:175], v[212:215], v[36:39]
	v_mfma_f32_16x16x32_bf16 v[32:35], v[180:183], v[212:215], v[32:35]
	s_barrier
	s_add_i32 s24, s46, s94
	s_add_u32 s98, s48, 0x80
	s_addc_u32 s99, s49, 0
	s_mov_b32 m0, s24
	ds_read_b128 v[184:187], v159 offset:49152
	global_load_lds_dwordx4 v132, s[98:99]
	s_add_i32 m0, s24, 0x2000
	s_add_u32 s24, s48, 0x80080
	s_addc_u32 s25, s49, 0
	s_add_i32 s46, s47, s94
	global_load_lds_dwordx4 v128, s[98:99]
	s_mov_b32 m0, s46
	ds_read_b128 v[188:191], v159 offset:50176
	global_load_lds_dwordx4 v132, s[24:25]
	s_add_i32 m0, s46, 0x2000
	ds_read_b128 v[192:195], v159 offset:51200
	global_load_lds_dwordx4 v128, s[24:25]
	s_add_u32 s100, s50, 0x80
	s_addc_u32 s101, s51, 0
	s_mov_b32 m0, s29
	ds_read_b128 v[196:199], v159 offset:52224
	global_load_lds_dwordx4 v134, s[100:101]
	s_mov_b32 m0, s34
	ds_read_b128 v[200:203], v159 offset:53248
	global_load_lds_dwordx4 v130, s[100:101]
	ds_read_b128 v[204:207], v159 offset:54272
	ds_read_b128 v[208:211], v159 offset:55296
	ds_read_b128 v[212:215], v159 offset:56320
	s_waitcnt vmcnt(8)
	s_waitcnt lgkmcnt(0)
	s_barrier
	s_waitcnt lgkmcnt(0)
	v_mfma_f32_16x16x32_bf16 v[92:95], v[144:147], v[184:187], v[92:95]
	v_mfma_f32_16x16x32_bf16 v[88:91], v[160:163], v[184:187], v[88:91]
	v_mfma_f32_16x16x32_bf16 v[84:87], v[144:147], v[192:195], v[84:87]
	v_mfma_f32_16x16x32_bf16 v[80:83], v[160:163], v[192:195], v[80:83]
	v_mfma_f32_16x16x32_bf16 v[72:75], v[144:147], v[200:203], v[72:75]
	v_mfma_f32_16x16x32_bf16 v[68:71], v[160:163], v[200:203], v[68:71]
	v_mfma_f32_16x16x32_bf16 v[60:63], v[144:147], v[208:211], v[60:63]
	v_mfma_f32_16x16x32_bf16 v[52:55], v[160:163], v[208:211], v[52:55]
	v_mfma_f32_16x16x32_bf16 v[92:95], v[148:151], v[188:191], v[92:95]
	v_mfma_f32_16x16x32_bf16 v[88:91], v[164:167], v[188:191], v[88:91]
	v_mfma_f32_16x16x32_bf16 v[84:87], v[148:151], v[196:199], v[84:87]
	v_mfma_f32_16x16x32_bf16 v[80:83], v[164:167], v[196:199], v[80:83]
	v_mfma_f32_16x16x32_bf16 v[72:75], v[148:151], v[204:207], v[72:75]
	v_mfma_f32_16x16x32_bf16 v[68:71], v[164:167], v[204:207], v[68:71]
	v_mfma_f32_16x16x32_bf16 v[60:63], v[148:151], v[212:215], v[60:63]
	v_mfma_f32_16x16x32_bf16 v[52:55], v[164:167], v[212:215], v[52:55]
	v_mfma_f32_16x16x32_bf16 v[28:31], v[168:171], v[184:187], v[28:31]
	v_mfma_f32_16x16x32_bf16 v[24:27], v[176:179], v[184:187], v[24:27]
	v_mfma_f32_16x16x32_bf16 v[20:23], v[168:171], v[192:195], v[20:23]
	v_mfma_f32_16x16x32_bf16 v[16:19], v[176:179], v[192:195], v[16:19]
	v_mfma_f32_16x16x32_bf16 v[12:15], v[168:171], v[200:203], v[12:15]
	v_mfma_f32_16x16x32_bf16 v[8:11], v[176:179], v[200:203], v[8:11]
	v_mfma_f32_16x16x32_bf16 v[4:7], v[168:171], v[208:211], v[4:7]
	v_mfma_f32_16x16x32_bf16 v[0:3], v[176:179], v[208:211], v[0:3]
	v_mfma_f32_16x16x32_bf16 v[28:31], v[172:175], v[188:191], v[28:31]
	v_mfma_f32_16x16x32_bf16 v[24:27], v[180:183], v[188:191], v[24:27]
	v_mfma_f32_16x16x32_bf16 v[20:23], v[172:175], v[196:199], v[20:23]
	v_mfma_f32_16x16x32_bf16 v[16:19], v[180:183], v[196:199], v[16:19]
	v_mfma_f32_16x16x32_bf16 v[12:15], v[172:175], v[204:207], v[12:15]
	v_mfma_f32_16x16x32_bf16 v[8:11], v[180:183], v[204:207], v[8:11]
	v_mfma_f32_16x16x32_bf16 v[4:7], v[172:175], v[212:215], v[4:7]
	v_mfma_f32_16x16x32_bf16 v[0:3], v[180:183], v[212:215], v[0:3]
	s_barrier
	s_add_i32 s54, s54, 2
	s_add_u32 s52, s52, 0x100
	s_addc_u32 s53, s53, 0
	s_cmp_gt_u32 s54, 29
	s_mov_b64 s[46:47], s[6:7]
	s_cbranch_scc0 .LBB0_1727
	s_and_b64 vcc, exec, s[22:23]
	s_cbranch_vccz .LBB0_1730
	s_barrier

; #define PG8_STAGE(bufoff, gbase, voff) do { _Pragma("unroll") for (int _i = 0; _i < 2; ++_i) \
;         __builtin_amdgcn_global_load_lds((const unsigned*)((const char*)(gbase) + (voff)[_i]), (LAS unsigned*)(lds + (bufoff) + ldsw + _i * 8192), 16, 0, 0); } while (0)
; #define PG8_LDA(dst, b, h) do { _Pragma("unroll") for (int m = 0; m < 4; ++m) _Pragma("unroll") for (int k = 0; k < 2; ++k) dst[m][k] = *(const LAS bf16x8*)(lds + PG8_SA(b, h) + aoff + m * 2048 + k * 1024); } while (0)
; #define PG8_LDB(dst, b, h) do { _Pragma("unroll") for (int n = 0; n < 2; ++n) _Pragma("unroll") for (int k = 0; k < 2; ++k) dst[n][k] = *(const LAS bf16x8*)(lds + PG8_SB(b, h) + boff + n * 2048 + k * 1024); } while (0)
; #define PG8_MMA(ai, bj, At, Bt) do { __builtin_amdgcn_s_setprio(1); _Pragma("unroll") for (int m = 0; m < 4; ++m) _Pragma("unroll") for (int n = 0; n < 2; ++n) _Pragma("unroll") for (int k = 0; k < 2; ++k) \
;         acc[ai][bj][m][n] = __builtin_amdgcn_mfma_f32_16x16x32_bf16(Bt[n][k], At[m][k], acc[ai][bj][m][n], 0, 0, 0); __builtin_amdgcn_s_setprio(0); } while (0)
; #define PG8_WAIT_V(n) asm volatile("s_waitcnt vmcnt(" #n ")" ::: "memory")
; #define PG8_WAIT_L(n) asm volatile("s_waitcnt lgkmcnt(" #n ")" ::: "memory")
; #define PG8_BAR __builtin_amdgcn_s_barrier()
; #define PG8_SCHED __builtin_amdgcn_sched_barrier(0)
; template <class Epi>
; __device__ __forceinline__ void gemm_phase(LAS unsigned char* lds, const Gemm g, const StaticOrder& S, const Epi& E, const int wid) {
;     ...
;             const bool last = (t == nt - 2);
;             const char* a1 = cA + (size_t)(t + 1) * kstep;
;             const char* a2 = last ? nA : cA + (size_t)(t + 2) * kstep; const char* b2 = last ? nB : cB + (size_t)(t + 2) * kstep;
;             const char* a3 = a2 + kstep; const char* b3 = b2 + kstep;
;             PG8_LDB(B0, 0, 0); PG8_LDB(B1, 0, 1); PG8_SCHED; PG8_LDA(At, 0, 0); PG8_STAGE(PG8_SA(1, 1), a1 + hstepA, voffA);
;             PG8_WAIT_V(8); PG8_WAIT_L(0); PG8_BAR; PG8_MMA(0, 0, At, B0); PG8_MMA(0, 1, At, B1); PG8_BAR; PG8_SCHED;
;             PG8_LDA(At, 0, 1); PG8_STAGE(PG8_SB(0, 0), b2, voffB); PG8_STAGE(PG8_SB(0, 1), b2 + hstepB, voffB); PG8_STAGE(PG8_SA(0, 0), a2, voffA);
;             PG8_WAIT_V(8); PG8_WAIT_L(0); PG8_BAR; PG8_MMA(1, 0, At, B0); PG8_MMA(1, 1, At, B1); PG8_BAR; PG8_SCHED;
.LBB0_1773:
	ds_read_b128 v[150:153], v147
	ds_read_b128 v[154:157], v147 offset:1024
	ds_read_b128 v[158:161], v147 offset:2048
	ds_read_b128 v[162:165], v147 offset:3072
	ds_read_b128 v[166:169], v148
	ds_read_b128 v[170:173], v148 offset:1024
	ds_read_b128 v[174:177], v148 offset:2048
	ds_read_b128 v[178:181], v148 offset:3072
	s_add_u32 s6, s42, 0x100
	s_addc_u32 s7, s43, 0
	s_cmp_eq_u32 s54, 28
	s_cselect_b32 s47, s21, s7
	s_cselect_b32 s46, s20, s6
	s_cselect_b32 s45, s19, s53
	s_cselect_b32 s44, s51, s52
	s_add_i32 m0, s15, 0xc000
	ds_read_b128 v[182:185], v149
	global_load_lds_dwordx4 v136, s[42:43]
	s_add_i32 m0, s15, 0xe000
	ds_read_b128 v[186:189], v149 offset:1024
	global_load_lds_dwordx4 v138, s[42:43]
	ds_read_b128 v[190:193], v149 offset:2048
	ds_read_b128 v[194:197], v149 offset:3072
	ds_read_b128 v[198:201], v149 offset:4096
	ds_read_b128 v[202:205], v149 offset:5120
	ds_read_b128 v[206:209], v149 offset:6144
	ds_read_b128 v[210:213], v149 offset:7168
	s_waitcnt vmcnt(8)
	s_waitcnt lgkmcnt(0)
	s_barrier
	s_waitcnt lgkmcnt(0)
	v_mfma_f32_16x16x32_bf16 v[124:127], v[150:153], v[182:185], v[124:127]
	v_mfma_f32_16x16x32_bf16 v[120:123], v[158:161], v[182:185], v[120:123]
	v_mfma_f32_16x16x32_bf16 v[108:111], v[150:153], v[190:193], v[108:111]
	v_mfma_f32_16x16x32_bf16 v[104:107], v[158:161], v[190:193], v[104:107]
	v_mfma_f32_16x16x32_bf16 v[92:95], v[150:153], v[198:201], v[92:95]
	v_mfma_f32_16x16x32_bf16 v[88:91], v[158:161], v[198:201], v[88:91]
	v_mfma_f32_16x16x32_bf16 v[76:79], v[150:153], v[206:209], v[76:79]
	v_mfma_f32_16x16x32_bf16 v[72:75], v[158:161], v[206:209], v[72:75]
	v_mfma_f32_16x16x32_bf16 v[124:127], v[154:157], v[186:189], v[124:127]
	v_mfma_f32_16x16x32_bf16 v[120:123], v[162:165], v[186:189], v[120:123]
	v_mfma_f32_16x16x32_bf16 v[108:111], v[154:157], v[194:197], v[108:111]
	v_mfma_f32_16x16x32_bf16 v[104:107], v[162:165], v[194:197], v[104:107]
	v_mfma_f32_16x16x32_bf16 v[92:95], v[154:157], v[202:205], v[92:95]
	v_mfma_f32_16x16x32_bf16 v[88:91], v[162:165], v[202:205], v[88:91]
	v_mfma_f32_16x16x32_bf16 v[76:79], v[154:157], v[210:213], v[76:79]
	v_mfma_f32_16x16x32_bf16 v[72:75], v[162:165], v[210:213], v[72:75]
	v_mfma_f32_16x16x32_bf16 v[116:119], v[166:169], v[182:185], v[116:119]
	v_mfma_f32_16x16x32_bf16 v[112:115], v[174:177], v[182:185], v[112:115]
	v_mfma_f32_16x16x32_bf16 v[100:103], v[166:169], v[190:193], v[100:103]
	v_mfma_f32_16x16x32_bf16 v[96:99], v[174:177], v[190:193], v[96:99]
	v_mfma_f32_16x16x32_bf16 v[84:87], v[166:169], v[198:201], v[84:87]
	v_mfma_f32_16x16x32_bf16 v[80:83], v[174:177], v[198:201], v[80:83]
	v_mfma_f32_16x16x32_bf16 v[68:71], v[166:169], v[206:209], v[68:71]
	v_mfma_f32_16x16x32_bf16 v[64:67], v[174:177], v[206:209], v[64:67]
	v_mfma_f32_16x16x32_bf16 v[116:119], v[170:173], v[186:189], v[116:119]
	v_mfma_f32_16x16x32_bf16 v[112:115], v[178:181], v[186:189], v[112:115]
	v_mfma_f32_16x16x32_bf16 v[100:103], v[170:173], v[194:197], v[100:103]
	v_mfma_f32_16x16x32_bf16 v[96:99], v[178:181], v[194:197], v[96:99]
	v_mfma_f32_16x16x32_bf16 v[84:87], v[170:173], v[202:205], v[84:87]
	v_mfma_f32_16x16x32_bf16 v[80:83], v[178:181], v[202:205], v[80:83]
	v_mfma_f32_16x16x32_bf16 v[68:71], v[170:173], v[210:213], v[68:71]
	v_mfma_f32_16x16x32_bf16 v[64:67], v[178:181], v[210:213], v[64:67]
	s_barrier
	s_add_i32 s24, s36, s94
	s_mov_b32 m0, s24
	ds_read_b128 v[182:185], v149 offset:16384
	global_load_lds_dwordx4 v132, s[44:45]
	s_add_i32 m0, s24, 0x2000
	s_add_u32 s24, s44, 0x80000
	s_addc_u32 s25, s45, 0
	s_add_i32 s42, s37, s94
	global_load_lds_dwordx4 v128, s[44:45]
	s_mov_b32 m0, s42
	ds_read_b128 v[186:189], v149 offset:17408
	global_load_lds_dwordx4 v132, s[24:25]
	s_add_i32 m0, s42, 0x2000
	ds_read_b128 v[190:193], v149 offset:18432
	global_load_lds_dwordx4 v128, s[24:25]
	s_mov_b32 m0, s15
	ds_read_b128 v[194:197], v149 offset:19456
	global_load_lds_dwordx4 v134, s[46:47]
	s_mov_b32 m0, s26
	ds_read_b128 v[198:201], v149 offset:20480
	global_load_lds_dwordx4 v130, s[46:47]
	ds_read_b128 v[202:205], v149 offset:21504
	ds_read_b128 v[206:209], v149 offset:22528
	ds_read_b128 v[210:213], v149 offset:23552
	s_waitcnt vmcnt(8)
	s_waitcnt lgkmcnt(0)
	s_barrier
	s_waitcnt lgkmcnt(0)
	v_mfma_f32_16x16x32_bf16 v[60:63], v[150:153], v[182:185], v[60:63]
	v_mfma_f32_16x16x32_bf16 v[56:59], v[158:161], v[182:185], v[56:59]
	v_mfma_f32_16x16x32_bf16 v[44:47], v[150:153], v[190:193], v[44:47]
	v_mfma_f32_16x16x32_bf16 v[40:43], v[158:161], v[190:193], v[40:43]
	v_mfma_f32_16x16x32_bf16 v[28:31], v[150:153], v[198:201], v[28:31]
	v_mfma_f32_16x16x32_bf16 v[24:27], v[158:161], v[198:201], v[24:27]
	v_mfma_f32_16x16x32_bf16 v[12:15], v[150:153], v[206:209], v[12:15]
	v_mfma_f32_16x16x32_bf16 v[8:11], v[158:161], v[206:209], v[8:11]
	v_mfma_f32_16x16x32_bf16 v[60:63], v[154:157], v[186:189], v[60:63]
	v_mfma_f32_16x16x32_bf16 v[56:59], v[162:165], v[186:189], v[56:59]
	v_mfma_f32_16x16x32_bf16 v[44:47], v[154:157], v[194:197], v[44:47]
	v_mfma_f32_16x16x32_bf16 v[40:43], v[162:165], v[194:197], v[40:43]
	v_mfma_f32_16x16x32_bf16 v[28:31], v[154:157], v[202:205], v[28:31]
	v_mfma_f32_16x16x32_bf16 v[24:27], v[162:165], v[202:205], v[24:27]
	v_mfma_f32_16x16x32_bf16 v[12:15], v[154:157], v[210:213], v[12:15]
	v_mfma_f32_16x16x32_bf16 v[8:11], v[162:165], v[210:213], v[8:11]
	v_mfma_f32_16x16x32_bf16 v[52:55], v[166:169], v[182:185], v[52:55]
	v_mfma_f32_16x16x32_bf16 v[48:51], v[174:177], v[182:185], v[48:51]
	v_mfma_f32_16x16x32_bf16 v[36:39], v[166:169], v[190:193], v[36:39]
	v_mfma_f32_16x16x32_bf16 v[32:35], v[174:177], v[190:193], v[32:35]
	v_mfma_f32_16x16x32_bf16 v[20:23], v[166:169], v[198:201], v[20:23]
	v_mfma_f32_16x16x32_bf16 v[16:19], v[174:177], v[198:201], v[16:19]
	v_mfma_f32_16x16x32_bf16 v[4:7], v[166:169], v[206:209], v[4:7]
	v_mfma_f32_16x16x32_bf16 v[0:3], v[174:177], v[206:209], v[0:3]
	v_mfma_f32_16x16x32_bf16 v[52:55], v[170:173], v[186:189], v[52:55]
	v_mfma_f32_16x16x32_bf16 v[48:51], v[178:181], v[186:189], v[48:51]
	v_mfma_f32_16x16x32_bf16 v[36:39], v[170:173], v[194:197], v[36:39]
	v_mfma_f32_16x16x32_bf16 v[32:35], v[178:181], v[194:197], v[32:35]
	v_mfma_f32_16x16x32_bf16 v[20:23], v[170:173], v[202:205], v[20:23]
	v_mfma_f32_16x16x32_bf16 v[16:19], v[178:181], v[202:205], v[16:19]
	v_mfma_f32_16x16x32_bf16 v[4:7], v[170:173], v[210:213], v[4:7]
	v_mfma_f32_16x16x32_bf16 v[0:3], v[178:181], v[210:213], v[0:3]
	s_barrier
; #define PG8_STAGE(bufoff, gbase, voff) do { _Pragma("unroll") for (int _i = 0; _i < 2; ++_i) \
;         __builtin_amdgcn_global_load_lds((const unsigned*)((const char*)(gbase) + (voff)[_i]), (LAS unsigned*)(lds + (bufoff) + ldsw + _i * 8192), 16, 0, 0); } while (0)
; #define PG8_LDA(dst, b, h) do { _Pragma("unroll") for (int m = 0; m < 4; ++m) _Pragma("unroll") for (int k = 0; k < 2; ++k) dst[m][k] = *(const LAS bf16x8*)(lds + PG8_SA(b, h) + aoff + m * 2048 + k * 1024); } while (0)
; #define PG8_LDB(dst, b, h) do { _Pragma("unroll") for (int n = 0; n < 2; ++n) _Pragma("unroll") for (int k = 0; k < 2; ++k) dst[n][k] = *(const LAS bf16x8*)(lds + PG8_SB(b, h) + boff + n * 2048 + k * 1024); } while (0)
; #define PG8_MMA(ai, bj, At, Bt) do { __builtin_amdgcn_s_setprio(1); _Pragma("unroll") for (int m = 0; m < 4; ++m) _Pragma("unroll") for (int n = 0; n < 2; ++n) _Pragma("unroll") for (int k = 0; k < 2; ++k) \
;         acc[ai][bj][m][n] = __builtin_amdgcn_mfma_f32_16x16x32_bf16(Bt[n][k], At[m][k], acc[ai][bj][m][n], 0, 0, 0); __builtin_amdgcn_s_setprio(0); } while (0)
; #define PG8_WAIT_V(n) asm volatile("s_waitcnt vmcnt(" #n ")" ::: "memory")
; #define PG8_WAIT_L(n) asm volatile("s_waitcnt lgkmcnt(" #n ")" ::: "memory")
; #define PG8_BAR __builtin_amdgcn_s_barrier()
; #define PG8_SCHED __builtin_amdgcn_sched_barrier(0)
; template <class Epi>
; __device__ __forceinline__ void gemm_phase(LAS unsigned char* lds, const Gemm g, const StaticOrder& S, const Epi& E, const int wid) {
;     ...
;             PG8_LDB(B0, 1, 0); PG8_LDB(B1, 1, 1); PG8_SCHED; PG8_LDA(At, 1, 0); PG8_STAGE(PG8_SA(0, 1), a2 + hstepA, voffA);
;             PG8_WAIT_V(8); PG8_WAIT_L(0); PG8_BAR; PG8_MMA(0, 0, At, B0); PG8_MMA(0, 1, At, B1); PG8_BAR; PG8_SCHED;
;             PG8_LDA(At, 1, 1); PG8_STAGE(PG8_SB(1, 0), b3, voffB); PG8_STAGE(PG8_SB(1, 1), b3 + hstepB, voffB); PG8_STAGE(PG8_SA(1, 0), a3, voffA);
;             PG8_WAIT_V(8); PG8_WAIT_L(0); PG8_BAR; PG8_MMA(1, 0, At, B0); PG8_MMA(1, 1, At, B1); PG8_BAR; PG8_SCHED;
;         }
;         if (wr == 0) PG8_BAR;
	s_add_i32 s42, 0, 0x18000
	s_add_i32 s43, 0, 0x1c000
	v_add_u32_e32 v162, s42, v144
	v_add_u32_e32 v178, s43, v144
	ds_read_b128 v[150:153], v162
	ds_read_b128 v[154:157], v162 offset:1024
	ds_read_b128 v[158:161], v162 offset:2048
	ds_read_b128 v[162:165], v162 offset:3072
	ds_read_b128 v[166:169], v178
	ds_read_b128 v[170:173], v178 offset:1024
	ds_read_b128 v[174:177], v178 offset:2048
	ds_read_b128 v[178:181], v178 offset:3072
	s_add_u32 s24, s46, 0x80000
	s_addc_u32 s25, s47, 0
	s_mov_b32 m0, s27
	ds_read_b128 v[182:185], v149 offset:32768
	global_load_lds_dwordx4 v134, s[24:25]
	s_mov_b32 m0, s28
	ds_read_b128 v[186:189], v149 offset:33792
	global_load_lds_dwordx4 v130, s[24:25]
	ds_read_b128 v[190:193], v149 offset:34816
	ds_read_b128 v[194:197], v149 offset:35840
	ds_read_b128 v[198:201], v149 offset:36864
	ds_read_b128 v[202:205], v149 offset:37888
	ds_read_b128 v[206:209], v149 offset:38912
	ds_read_b128 v[210:213], v149 offset:39936
	s_waitcnt vmcnt(8)
	s_waitcnt lgkmcnt(0)
	s_barrier
	s_waitcnt lgkmcnt(0)
	v_mfma_f32_16x16x32_bf16 v[124:127], v[150:153], v[182:185], v[124:127]
	v_mfma_f32_16x16x32_bf16 v[120:123], v[158:161], v[182:185], v[120:123]
	v_mfma_f32_16x16x32_bf16 v[108:111], v[150:153], v[190:193], v[108:111]
	v_mfma_f32_16x16x32_bf16 v[104:107], v[158:161], v[190:193], v[104:107]
	v_mfma_f32_16x16x32_bf16 v[92:95], v[150:153], v[198:201], v[92:95]
	v_mfma_f32_16x16x32_bf16 v[88:91], v[158:161], v[198:201], v[88:91]
	v_mfma_f32_16x16x32_bf16 v[76:79], v[150:153], v[206:209], v[76:79]
	v_mfma_f32_16x16x32_bf16 v[72:75], v[158:161], v[206:209], v[72:75]
	v_mfma_f32_16x16x32_bf16 v[124:127], v[154:157], v[186:189], v[124:127]
	v_mfma_f32_16x16x32_bf16 v[120:123], v[162:165], v[186:189], v[120:123]
	v_mfma_f32_16x16x32_bf16 v[108:111], v[154:157], v[194:197], v[108:111]
	v_mfma_f32_16x16x32_bf16 v[104:107], v[162:165], v[194:197], v[104:107]
	v_mfma_f32_16x16x32_bf16 v[92:95], v[154:157], v[202:205], v[92:95]
	v_mfma_f32_16x16x32_bf16 v[88:91], v[162:165], v[202:205], v[88:91]
	v_mfma_f32_16x16x32_bf16 v[76:79], v[154:157], v[210:213], v[76:79]
	v_mfma_f32_16x16x32_bf16 v[72:75], v[162:165], v[210:213], v[72:75]
	v_mfma_f32_16x16x32_bf16 v[116:119], v[166:169], v[182:185], v[116:119]
	v_mfma_f32_16x16x32_bf16 v[112:115], v[174:177], v[182:185], v[112:115]
	v_mfma_f32_16x16x32_bf16 v[100:103], v[166:169], v[190:193], v[100:103]
	v_mfma_f32_16x16x32_bf16 v[96:99], v[174:177], v[190:193], v[96:99]
	v_mfma_f32_16x16x32_bf16 v[84:87], v[166:169], v[198:201], v[84:87]
	v_mfma_f32_16x16x32_bf16 v[80:83], v[174:177], v[198:201], v[80:83]
	v_mfma_f32_16x16x32_bf16 v[68:71], v[166:169], v[206:209], v[68:71]
	v_mfma_f32_16x16x32_bf16 v[64:67], v[174:177], v[206:209], v[64:67]
	v_mfma_f32_16x16x32_bf16 v[116:119], v[170:173], v[186:189], v[116:119]
	v_mfma_f32_16x16x32_bf16 v[112:115], v[178:181], v[186:189], v[112:115]
	v_mfma_f32_16x16x32_bf16 v[100:103], v[170:173], v[194:197], v[100:103]
	v_mfma_f32_16x16x32_bf16 v[96:99], v[178:181], v[194:197], v[96:99]
	v_mfma_f32_16x16x32_bf16 v[84:87], v[170:173], v[202:205], v[84:87]
	v_mfma_f32_16x16x32_bf16 v[80:83], v[178:181], v[202:205], v[80:83]
	v_mfma_f32_16x16x32_bf16 v[68:71], v[170:173], v[210:213], v[68:71]
	v_mfma_f32_16x16x32_bf16 v[64:67], v[178:181], v[210:213], v[64:67]
	s_barrier
	s_add_i32 s24, s42, s94
	s_add_u32 s98, s44, 0x80
	s_addc_u32 s99, s45, 0
	s_mov_b32 m0, s24
	ds_read_b128 v[182:185], v149 offset:49152
	global_load_lds_dwordx4 v132, s[98:99]
	s_add_i32 m0, s24, 0x2000
	s_add_u32 s24, s44, 0x80080
	s_addc_u32 s25, s45, 0
	s_add_i32 s42, s43, s94
	global_load_lds_dwordx4 v128, s[98:99]
	s_mov_b32 m0, s42
	ds_read_b128 v[186:189], v149 offset:50176
	global_load_lds_dwordx4 v132, s[24:25]
	s_add_i32 m0, s42, 0x2000
	ds_read_b128 v[190:193], v149 offset:51200
	global_load_lds_dwordx4 v128, s[24:25]
	s_add_u32 s100, s46, 0x80
	s_addc_u32 s101, s47, 0
	s_mov_b32 m0, s34
	ds_read_b128 v[194:197], v149 offset:52224
	global_load_lds_dwordx4 v134, s[100:101]
	s_mov_b32 m0, s35
	ds_read_b128 v[198:201], v149 offset:53248
	global_load_lds_dwordx4 v130, s[100:101]
	ds_read_b128 v[202:205], v149 offset:54272
	ds_read_b128 v[206:209], v149 offset:55296
	ds_read_b128 v[210:213], v149 offset:56320
	s_waitcnt vmcnt(8)
	s_waitcnt lgkmcnt(0)
	s_barrier
	s_waitcnt lgkmcnt(0)
	v_mfma_f32_16x16x32_bf16 v[60:63], v[150:153], v[182:185], v[60:63]
	v_mfma_f32_16x16x32_bf16 v[56:59], v[158:161], v[182:185], v[56:59]
	v_mfma_f32_16x16x32_bf16 v[44:47], v[150:153], v[190:193], v[44:47]
	v_mfma_f32_16x16x32_bf16 v[40:43], v[158:161], v[190:193], v[40:43]
	v_mfma_f32_16x16x32_bf16 v[28:31], v[150:153], v[198:201], v[28:31]
	v_mfma_f32_16x16x32_bf16 v[24:27], v[158:161], v[198:201], v[24:27]
	v_mfma_f32_16x16x32_bf16 v[12:15], v[150:153], v[206:209], v[12:15]
	v_mfma_f32_16x16x32_bf16 v[8:11], v[158:161], v[206:209], v[8:11]
	v_mfma_f32_16x16x32_bf16 v[60:63], v[154:157], v[186:189], v[60:63]
	v_mfma_f32_16x16x32_bf16 v[56:59], v[162:165], v[186:189], v[56:59]
	v_mfma_f32_16x16x32_bf16 v[44:47], v[154:157], v[194:197], v[44:47]
	v_mfma_f32_16x16x32_bf16 v[40:43], v[162:165], v[194:197], v[40:43]
	v_mfma_f32_16x16x32_bf16 v[28:31], v[154:157], v[202:205], v[28:31]
	v_mfma_f32_16x16x32_bf16 v[24:27], v[162:165], v[202:205], v[24:27]
	v_mfma_f32_16x16x32_bf16 v[12:15], v[154:157], v[210:213], v[12:15]
	v_mfma_f32_16x16x32_bf16 v[8:11], v[162:165], v[210:213], v[8:11]
	v_mfma_f32_16x16x32_bf16 v[52:55], v[166:169], v[182:185], v[52:55]
	v_mfma_f32_16x16x32_bf16 v[48:51], v[174:177], v[182:185], v[48:51]
	v_mfma_f32_16x16x32_bf16 v[36:39], v[166:169], v[190:193], v[36:39]
	v_mfma_f32_16x16x32_bf16 v[32:35], v[174:177], v[190:193], v[32:35]
	v_mfma_f32_16x16x32_bf16 v[20:23], v[166:169], v[198:201], v[20:23]
	v_mfma_f32_16x16x32_bf16 v[16:19], v[174:177], v[198:201], v[16:19]
	v_mfma_f32_16x16x32_bf16 v[4:7], v[166:169], v[206:209], v[4:7]
	v_mfma_f32_16x16x32_bf16 v[0:3], v[174:177], v[206:209], v[0:3]
	v_mfma_f32_16x16x32_bf16 v[52:55], v[170:173], v[186:189], v[52:55]
	v_mfma_f32_16x16x32_bf16 v[48:51], v[178:181], v[186:189], v[48:51]
	v_mfma_f32_16x16x32_bf16 v[36:39], v[170:173], v[194:197], v[36:39]
	v_mfma_f32_16x16x32_bf16 v[32:35], v[178:181], v[194:197], v[32:35]
	v_mfma_f32_16x16x32_bf16 v[20:23], v[170:173], v[202:205], v[20:23]
	v_mfma_f32_16x16x32_bf16 v[16:19], v[178:181], v[202:205], v[16:19]
	v_mfma_f32_16x16x32_bf16 v[4:7], v[170:173], v[210:213], v[4:7]
	v_mfma_f32_16x16x32_bf16 v[0:3], v[178:181], v[210:213], v[0:3]
	s_barrier
	s_add_i32 s54, s54, 2
	s_add_u32 s52, s52, 0x100
	s_addc_u32 s53, s53, 0
	s_cmp_gt_u32 s54, 29
	s_mov_b64 s[42:43], s[6:7]
	s_cbranch_scc0 .LBB0_1773
	s_and_b64 vcc, exec, s[22:23]
	s_cbranch_vccz .LBB0_1776
	s_barrier

; #define PG8_STAGE(bufoff, gbase, voff) do { _Pragma("unroll") for (int _i = 0; _i < 2; ++_i) \
;         __builtin_amdgcn_global_load_lds((const unsigned*)((const char*)(gbase) + (voff)[_i]), (LAS unsigned*)(lds + (bufoff) + ldsw + _i * 8192), 16, 0, 0); } while (0)
; #define PG8_LDA(dst, b, h) do { _Pragma("unroll") for (int m = 0; m < 4; ++m) _Pragma("unroll") for (int k = 0; k < 2; ++k) dst[m][k] = *(const LAS bf16x8*)(lds + PG8_SA(b, h) + aoff + m * 2048 + k * 1024); } while (0)
; #define PG8_LDB(dst, b, h) do { _Pragma("unroll") for (int n = 0; n < 2; ++n) _Pragma("unroll") for (int k = 0; k < 2; ++k) dst[n][k] = *(const LAS bf16x8*)(lds + PG8_SB(b, h) + boff + n * 2048 + k * 1024); } while (0)
; #define PG8_MMA(ai, bj, At, Bt) do { __builtin_amdgcn_s_setprio(1); _Pragma("unroll") for (int m = 0; m < 4; ++m) _Pragma("unroll") for (int n = 0; n < 2; ++n) _Pragma("unroll") for (int k = 0; k < 2; ++k) \
;         acc[ai][bj][m][n] = __builtin_amdgcn_mfma_f32_16x16x32_bf16(Bt[n][k], At[m][k], acc[ai][bj][m][n], 0, 0, 0); __builtin_amdgcn_s_setprio(0); } while (0)
; #define PG8_WAIT_V(n) asm volatile("s_waitcnt vmcnt(" #n ")" ::: "memory")
; #define PG8_WAIT_L(n) asm volatile("s_waitcnt lgkmcnt(" #n ")" ::: "memory")
; #define PG8_BAR __builtin_amdgcn_s_barrier()
; #define PG8_SCHED __builtin_amdgcn_sched_barrier(0)
; template <class Epi>
; __device__ __forceinline__ void gemm_phase(LAS unsigned char* lds, const Gemm g, const StaticOrder& S, const Epi& E, const int wid) {
;     ...
;             const bool last = (t == nt - 2);
;             const char* a1 = cA + (size_t)(t + 1) * kstep;
;             const char* a2 = last ? nA : cA + (size_t)(t + 2) * kstep; const char* b2 = last ? nB : cB + (size_t)(t + 2) * kstep;
;             const char* a3 = a2 + kstep; const char* b3 = b2 + kstep;
;             PG8_LDB(B0, 0, 0); PG8_LDB(B1, 0, 1); PG8_SCHED; PG8_LDA(At, 0, 0); PG8_STAGE(PG8_SA(1, 1), a1 + hstepA, voffA);
;             PG8_WAIT_V(8); PG8_WAIT_L(0); PG8_BAR; PG8_MMA(0, 0, At, B0); PG8_MMA(0, 1, At, B1); PG8_BAR; PG8_SCHED;
;             PG8_LDA(At, 0, 1); PG8_STAGE(PG8_SB(0, 0), b2, voffB); PG8_STAGE(PG8_SB(0, 1), b2 + hstepB, voffB); PG8_STAGE(PG8_SA(0, 0), a2, voffA);
;             PG8_WAIT_V(8); PG8_WAIT_L(0); PG8_BAR; PG8_MMA(1, 0, At, B0); PG8_MMA(1, 1, At, B1); PG8_BAR; PG8_SCHED;
.LBB0_1810:
	ds_read_b128 v[144:147], v153
	ds_read_b128 v[156:159], v153 offset:1024
	ds_read_b128 v[160:163], v153 offset:2048
	ds_read_b128 v[164:167], v153 offset:3072
	ds_read_b128 v[168:171], v154
	ds_read_b128 v[172:175], v154 offset:1024
	ds_read_b128 v[176:179], v154 offset:2048
	ds_read_b128 v[180:183], v154 offset:3072
	s_add_u32 s26, s20, 0x100
	s_addc_u32 s27, s21, 0
	s_cmpk_eq_i32 s45, 0x54
	s_cselect_b32 s31, s7, s27
	s_cselect_b32 s30, s6, s26
	s_cselect_b32 s29, s19, s44
	s_cselect_b32 s28, s18, s43
	s_add_i32 m0, s1, 0xc000
	ds_read_b128 v[184:187], v155
	global_load_lds_dwordx4 v136, s[20:21]
	s_add_i32 m0, s1, 0xe000
	ds_read_b128 v[188:191], v155 offset:1024
	global_load_lds_dwordx4 v138, s[20:21]
	ds_read_b128 v[192:195], v155 offset:2048
	ds_read_b128 v[196:199], v155 offset:3072
	ds_read_b128 v[200:203], v155 offset:4096
	ds_read_b128 v[204:207], v155 offset:5120
	ds_read_b128 v[208:211], v155 offset:6144
	ds_read_b128 v[212:215], v155 offset:7168
	s_waitcnt vmcnt(8)
	s_waitcnt lgkmcnt(0)
	s_barrier
	s_waitcnt lgkmcnt(0)
	v_mfma_f32_16x16x32_bf16 v[124:127], v[144:147], v[184:187], v[124:127]
	v_mfma_f32_16x16x32_bf16 v[120:123], v[160:163], v[184:187], v[120:123]
	v_mfma_f32_16x16x32_bf16 v[116:119], v[144:147], v[192:195], v[116:119]
	v_mfma_f32_16x16x32_bf16 v[112:115], v[160:163], v[192:195], v[112:115]
	v_mfma_f32_16x16x32_bf16 v[108:111], v[144:147], v[200:203], v[108:111]
	v_mfma_f32_16x16x32_bf16 v[104:107], v[160:163], v[200:203], v[104:107]
	v_mfma_f32_16x16x32_bf16 v[100:103], v[144:147], v[208:211], v[100:103]
	v_mfma_f32_16x16x32_bf16 v[96:99], v[160:163], v[208:211], v[96:99]
	v_mfma_f32_16x16x32_bf16 v[124:127], v[156:159], v[188:191], v[124:127]
	v_mfma_f32_16x16x32_bf16 v[120:123], v[164:167], v[188:191], v[120:123]
	v_mfma_f32_16x16x32_bf16 v[116:119], v[156:159], v[196:199], v[116:119]
	v_mfma_f32_16x16x32_bf16 v[112:115], v[164:167], v[196:199], v[112:115]
	v_mfma_f32_16x16x32_bf16 v[108:111], v[156:159], v[204:207], v[108:111]
	v_mfma_f32_16x16x32_bf16 v[104:107], v[164:167], v[204:207], v[104:107]
	v_mfma_f32_16x16x32_bf16 v[100:103], v[156:159], v[212:215], v[100:103]
	v_mfma_f32_16x16x32_bf16 v[96:99], v[164:167], v[212:215], v[96:99]
	v_mfma_f32_16x16x32_bf16 v[68:71], v[168:171], v[184:187], v[68:71]
	v_mfma_f32_16x16x32_bf16 v[64:67], v[176:179], v[184:187], v[64:67]
	v_mfma_f32_16x16x32_bf16 v[52:55], v[168:171], v[192:195], v[52:55]
	v_mfma_f32_16x16x32_bf16 v[48:51], v[176:179], v[192:195], v[48:51]
	v_mfma_f32_16x16x32_bf16 v[44:47], v[168:171], v[200:203], v[44:47]
	v_mfma_f32_16x16x32_bf16 v[40:43], v[176:179], v[200:203], v[40:43]
	v_mfma_f32_16x16x32_bf16 v[36:39], v[168:171], v[208:211], v[36:39]
	v_mfma_f32_16x16x32_bf16 v[32:35], v[176:179], v[208:211], v[32:35]
	v_mfma_f32_16x16x32_bf16 v[68:71], v[172:175], v[188:191], v[68:71]
	v_mfma_f32_16x16x32_bf16 v[64:67], v[180:183], v[188:191], v[64:67]
	v_mfma_f32_16x16x32_bf16 v[52:55], v[172:175], v[196:199], v[52:55]
	v_mfma_f32_16x16x32_bf16 v[48:51], v[180:183], v[196:199], v[48:51]
	v_mfma_f32_16x16x32_bf16 v[44:47], v[172:175], v[204:207], v[44:47]
	v_mfma_f32_16x16x32_bf16 v[40:43], v[180:183], v[204:207], v[40:43]
	v_mfma_f32_16x16x32_bf16 v[36:39], v[172:175], v[212:215], v[36:39]
	v_mfma_f32_16x16x32_bf16 v[32:35], v[180:183], v[212:215], v[32:35]
	s_barrier
	s_add_i32 s20, s0, s94
	s_mov_b32 m0, s20
	ds_read_b128 v[184:187], v155 offset:16384
	global_load_lds_dwordx4 v132, s[28:29]
	s_add_i32 m0, s20, 0x2000
	s_add_u32 s20, s28, 0x160000
	s_addc_u32 s21, s29, 0
	s_add_i32 s24, s38, s94
	global_load_lds_dwordx4 v128, s[28:29]
	s_mov_b32 m0, s24
	ds_read_b128 v[188:191], v155 offset:17408
	global_load_lds_dwordx4 v132, s[20:21]
	s_add_i32 m0, s24, 0x2000
	ds_read_b128 v[192:195], v155 offset:18432
	global_load_lds_dwordx4 v128, s[20:21]
	s_mov_b32 m0, s1
	ds_read_b128 v[196:199], v155 offset:19456
	global_load_lds_dwordx4 v134, s[30:31]
	s_mov_b32 m0, s12
	ds_read_b128 v[200:203], v155 offset:20480
	global_load_lds_dwordx4 v130, s[30:31]
	ds_read_b128 v[204:207], v155 offset:21504
	ds_read_b128 v[208:211], v155 offset:22528
	ds_read_b128 v[212:215], v155 offset:23552
	s_waitcnt vmcnt(8)
	s_waitcnt lgkmcnt(0)
	s_barrier
	s_waitcnt lgkmcnt(0)
	v_mfma_f32_16x16x32_bf16 v[92:95], v[144:147], v[184:187], v[92:95]
	v_mfma_f32_16x16x32_bf16 v[88:91], v[160:163], v[184:187], v[88:91]
	v_mfma_f32_16x16x32_bf16 v[84:87], v[144:147], v[192:195], v[84:87]
	v_mfma_f32_16x16x32_bf16 v[80:83], v[160:163], v[192:195], v[80:83]
	v_mfma_f32_16x16x32_bf16 v[76:79], v[144:147], v[200:203], v[76:79]
	v_mfma_f32_16x16x32_bf16 v[72:75], v[160:163], v[200:203], v[72:75]
	v_mfma_f32_16x16x32_bf16 v[60:63], v[144:147], v[208:211], v[60:63]
	v_mfma_f32_16x16x32_bf16 v[56:59], v[160:163], v[208:211], v[56:59]
	v_mfma_f32_16x16x32_bf16 v[92:95], v[156:159], v[188:191], v[92:95]
	v_mfma_f32_16x16x32_bf16 v[88:91], v[164:167], v[188:191], v[88:91]
	v_mfma_f32_16x16x32_bf16 v[84:87], v[156:159], v[196:199], v[84:87]
	v_mfma_f32_16x16x32_bf16 v[80:83], v[164:167], v[196:199], v[80:83]
	v_mfma_f32_16x16x32_bf16 v[76:79], v[156:159], v[204:207], v[76:79]
	v_mfma_f32_16x16x32_bf16 v[72:75], v[164:167], v[204:207], v[72:75]
	v_mfma_f32_16x16x32_bf16 v[60:63], v[156:159], v[212:215], v[60:63]
	v_mfma_f32_16x16x32_bf16 v[56:59], v[164:167], v[212:215], v[56:59]
	v_mfma_f32_16x16x32_bf16 v[28:31], v[168:171], v[184:187], v[28:31]
	v_mfma_f32_16x16x32_bf16 v[24:27], v[176:179], v[184:187], v[24:27]
	v_mfma_f32_16x16x32_bf16 v[20:23], v[168:171], v[192:195], v[20:23]
	v_mfma_f32_16x16x32_bf16 v[16:19], v[176:179], v[192:195], v[16:19]
	v_mfma_f32_16x16x32_bf16 v[12:15], v[168:171], v[200:203], v[12:15]
	v_mfma_f32_16x16x32_bf16 v[8:11], v[176:179], v[200:203], v[8:11]
	v_mfma_f32_16x16x32_bf16 v[4:7], v[168:171], v[208:211], v[4:7]
	v_mfma_f32_16x16x32_bf16 v[0:3], v[176:179], v[208:211], v[0:3]
	v_mfma_f32_16x16x32_bf16 v[28:31], v[172:175], v[188:191], v[28:31]
	v_mfma_f32_16x16x32_bf16 v[24:27], v[180:183], v[188:191], v[24:27]
	v_mfma_f32_16x16x32_bf16 v[20:23], v[172:175], v[196:199], v[20:23]
	v_mfma_f32_16x16x32_bf16 v[16:19], v[180:183], v[196:199], v[16:19]
	v_mfma_f32_16x16x32_bf16 v[12:15], v[172:175], v[204:207], v[12:15]
	v_mfma_f32_16x16x32_bf16 v[8:11], v[180:183], v[204:207], v[8:11]
	v_mfma_f32_16x16x32_bf16 v[4:7], v[172:175], v[212:215], v[4:7]
	v_mfma_f32_16x16x32_bf16 v[0:3], v[180:183], v[212:215], v[0:3]
	s_barrier
; #define PG8_STAGE(bufoff, gbase, voff) do { _Pragma("unroll") for (int _i = 0; _i < 2; ++_i) \
;         __builtin_amdgcn_global_load_lds((const unsigned*)((const char*)(gbase) + (voff)[_i]), (LAS unsigned*)(lds + (bufoff) + ldsw + _i * 8192), 16, 0, 0); } while (0)
; #define PG8_LDA(dst, b, h) do { _Pragma("unroll") for (int m = 0; m < 4; ++m) _Pragma("unroll") for (int k = 0; k < 2; ++k) dst[m][k] = *(const LAS bf16x8*)(lds + PG8_SA(b, h) + aoff + m * 2048 + k * 1024); } while (0)
; #define PG8_LDB(dst, b, h) do { _Pragma("unroll") for (int n = 0; n < 2; ++n) _Pragma("unroll") for (int k = 0; k < 2; ++k) dst[n][k] = *(const LAS bf16x8*)(lds + PG8_SB(b, h) + boff + n * 2048 + k * 1024); } while (0)
; #define PG8_MMA(ai, bj, At, Bt) do { __builtin_amdgcn_s_setprio(1); _Pragma("unroll") for (int m = 0; m < 4; ++m) _Pragma("unroll") for (int n = 0; n < 2; ++n) _Pragma("unroll") for (int k = 0; k < 2; ++k) \
;         acc[ai][bj][m][n] = __builtin_amdgcn_mfma_f32_16x16x32_bf16(Bt[n][k], At[m][k], acc[ai][bj][m][n], 0, 0, 0); __builtin_amdgcn_s_setprio(0); } while (0)
; #define PG8_WAIT_V(n) asm volatile("s_waitcnt vmcnt(" #n ")" ::: "memory")
; #define PG8_WAIT_L(n) asm volatile("s_waitcnt lgkmcnt(" #n ")" ::: "memory")
; #define PG8_BAR __builtin_amdgcn_s_barrier()
; #define PG8_SCHED __builtin_amdgcn_sched_barrier(0)
; template <class Epi>
; __device__ __forceinline__ void gemm_phase(LAS unsigned char* lds, const Gemm g, const StaticOrder& S, const Epi& E, const int wid) {
;     ...
;             PG8_LDB(B0, 1, 0); PG8_LDB(B1, 1, 1); PG8_SCHED; PG8_LDA(At, 1, 0); PG8_STAGE(PG8_SA(0, 1), a2 + hstepA, voffA);
;             PG8_WAIT_V(8); PG8_WAIT_L(0); PG8_BAR; PG8_MMA(0, 0, At, B0); PG8_MMA(0, 1, At, B1); PG8_BAR; PG8_SCHED;
;             PG8_LDA(At, 1, 1); PG8_STAGE(PG8_SB(1, 0), b3, voffB); PG8_STAGE(PG8_SB(1, 1), b3 + hstepB, voffB); PG8_STAGE(PG8_SA(1, 0), a3, voffA);
;             PG8_WAIT_V(8); PG8_WAIT_L(0); PG8_BAR; PG8_MMA(1, 0, At, B0); PG8_MMA(1, 1, At, B1); PG8_BAR; PG8_SCHED;
;         }
;         if (wr == 0) PG8_BAR;
	s_add_i32 s24, 0, 0x18000
	s_add_i32 s25, 0, 0x1c000
	v_add_u32_e32 v164, s24, v150
	v_add_u32_e32 v180, s25, v150
	ds_read_b128 v[144:147], v164
	ds_read_b128 v[156:159], v164 offset:1024
	ds_read_b128 v[160:163], v164 offset:2048
	ds_read_b128 v[164:167], v164 offset:3072
	ds_read_b128 v[168:171], v180
	ds_read_b128 v[172:175], v180 offset:1024
	ds_read_b128 v[176:179], v180 offset:2048
	ds_read_b128 v[180:183], v180 offset:3072
	s_add_u32 s20, s30, 0x160000
	s_addc_u32 s21, s31, 0
	s_mov_b32 m0, s15
	ds_read_b128 v[184:187], v155 offset:32768
	global_load_lds_dwordx4 v134, s[20:21]
	s_mov_b32 m0, s34
	ds_read_b128 v[188:191], v155 offset:33792
	global_load_lds_dwordx4 v130, s[20:21]
	ds_read_b128 v[192:195], v155 offset:34816
	ds_read_b128 v[196:199], v155 offset:35840
	ds_read_b128 v[200:203], v155 offset:36864
	ds_read_b128 v[204:207], v155 offset:37888
	ds_read_b128 v[208:211], v155 offset:38912
	ds_read_b128 v[212:215], v155 offset:39936
	s_waitcnt vmcnt(8)
	s_waitcnt lgkmcnt(0)
	s_barrier
	s_waitcnt lgkmcnt(0)
	v_mfma_f32_16x16x32_bf16 v[124:127], v[144:147], v[184:187], v[124:127]
	v_mfma_f32_16x16x32_bf16 v[120:123], v[160:163], v[184:187], v[120:123]
	v_mfma_f32_16x16x32_bf16 v[116:119], v[144:147], v[192:195], v[116:119]
	v_mfma_f32_16x16x32_bf16 v[112:115], v[160:163], v[192:195], v[112:115]
	v_mfma_f32_16x16x32_bf16 v[108:111], v[144:147], v[200:203], v[108:111]
	v_mfma_f32_16x16x32_bf16 v[104:107], v[160:163], v[200:203], v[104:107]
	v_mfma_f32_16x16x32_bf16 v[100:103], v[144:147], v[208:211], v[100:103]
	v_mfma_f32_16x16x32_bf16 v[96:99], v[160:163], v[208:211], v[96:99]
	v_mfma_f32_16x16x32_bf16 v[124:127], v[156:159], v[188:191], v[124:127]
	v_mfma_f32_16x16x32_bf16 v[120:123], v[164:167], v[188:191], v[120:123]
	v_mfma_f32_16x16x32_bf16 v[116:119], v[156:159], v[196:199], v[116:119]
	v_mfma_f32_16x16x32_bf16 v[112:115], v[164:167], v[196:199], v[112:115]
	v_mfma_f32_16x16x32_bf16 v[108:111], v[156:159], v[204:207], v[108:111]
	v_mfma_f32_16x16x32_bf16 v[104:107], v[164:167], v[204:207], v[104:107]
	v_mfma_f32_16x16x32_bf16 v[100:103], v[156:159], v[212:215], v[100:103]
	v_mfma_f32_16x16x32_bf16 v[96:99], v[164:167], v[212:215], v[96:99]
	v_mfma_f32_16x16x32_bf16 v[68:71], v[168:171], v[184:187], v[68:71]
	v_mfma_f32_16x16x32_bf16 v[64:67], v[176:179], v[184:187], v[64:67]
	v_mfma_f32_16x16x32_bf16 v[52:55], v[168:171], v[192:195], v[52:55]
	v_mfma_f32_16x16x32_bf16 v[48:51], v[176:179], v[192:195], v[48:51]
	v_mfma_f32_16x16x32_bf16 v[44:47], v[168:171], v[200:203], v[44:47]
	v_mfma_f32_16x16x32_bf16 v[40:43], v[176:179], v[200:203], v[40:43]
	v_mfma_f32_16x16x32_bf16 v[36:39], v[168:171], v[208:211], v[36:39]
	v_mfma_f32_16x16x32_bf16 v[32:35], v[176:179], v[208:211], v[32:35]
	v_mfma_f32_16x16x32_bf16 v[68:71], v[172:175], v[188:191], v[68:71]
	v_mfma_f32_16x16x32_bf16 v[64:67], v[180:183], v[188:191], v[64:67]
	v_mfma_f32_16x16x32_bf16 v[52:55], v[172:175], v[196:199], v[52:55]
	v_mfma_f32_16x16x32_bf16 v[48:51], v[180:183], v[196:199], v[48:51]
	v_mfma_f32_16x16x32_bf16 v[44:47], v[172:175], v[204:207], v[44:47]
	v_mfma_f32_16x16x32_bf16 v[40:43], v[180:183], v[204:207], v[40:43]
	v_mfma_f32_16x16x32_bf16 v[36:39], v[172:175], v[212:215], v[36:39]
	v_mfma_f32_16x16x32_bf16 v[32:35], v[180:183], v[212:215], v[32:35]
	s_barrier
	s_add_i32 s20, s24, s94
	s_add_u32 s98, s28, 0x80
	s_addc_u32 s99, s29, 0
	s_mov_b32 m0, s20
	ds_read_b128 v[184:187], v155 offset:49152
	global_load_lds_dwordx4 v132, s[98:99]
	s_add_i32 m0, s20, 0x2000
	s_add_u32 s20, s28, 0x160080
	s_addc_u32 s21, s29, 0
	s_add_i32 s24, s25, s94
	global_load_lds_dwordx4 v128, s[98:99]
	s_mov_b32 m0, s24
	ds_read_b128 v[188:191], v155 offset:50176
	global_load_lds_dwordx4 v132, s[20:21]
	s_add_i32 m0, s24, 0x2000
	ds_read_b128 v[192:195], v155 offset:51200
	global_load_lds_dwordx4 v128, s[20:21]
	s_add_u32 s100, s30, 0x80
	s_addc_u32 s101, s31, 0
	s_mov_b32 m0, s36
	ds_read_b128 v[196:199], v155 offset:52224
	global_load_lds_dwordx4 v134, s[100:101]
	s_mov_b32 m0, s37
	ds_read_b128 v[200:203], v155 offset:53248
	global_load_lds_dwordx4 v130, s[100:101]
	ds_read_b128 v[204:207], v155 offset:54272
	ds_read_b128 v[208:211], v155 offset:55296
	ds_read_b128 v[212:215], v155 offset:56320
	s_waitcnt vmcnt(8)
	s_waitcnt lgkmcnt(0)
	s_barrier
	s_waitcnt lgkmcnt(0)
	v_mfma_f32_16x16x32_bf16 v[92:95], v[144:147], v[184:187], v[92:95]
	v_mfma_f32_16x16x32_bf16 v[88:91], v[160:163], v[184:187], v[88:91]
	v_mfma_f32_16x16x32_bf16 v[84:87], v[144:147], v[192:195], v[84:87]
	v_mfma_f32_16x16x32_bf16 v[80:83], v[160:163], v[192:195], v[80:83]
	v_mfma_f32_16x16x32_bf16 v[76:79], v[144:147], v[200:203], v[76:79]
	v_mfma_f32_16x16x32_bf16 v[72:75], v[160:163], v[200:203], v[72:75]
	v_mfma_f32_16x16x32_bf16 v[60:63], v[144:147], v[208:211], v[60:63]
	v_mfma_f32_16x16x32_bf16 v[56:59], v[160:163], v[208:211], v[56:59]
	v_mfma_f32_16x16x32_bf16 v[92:95], v[156:159], v[188:191], v[92:95]
	v_mfma_f32_16x16x32_bf16 v[88:91], v[164:167], v[188:191], v[88:91]
	v_mfma_f32_16x16x32_bf16 v[84:87], v[156:159], v[196:199], v[84:87]
	v_mfma_f32_16x16x32_bf16 v[80:83], v[164:167], v[196:199], v[80:83]
	v_mfma_f32_16x16x32_bf16 v[76:79], v[156:159], v[204:207], v[76:79]
	v_mfma_f32_16x16x32_bf16 v[72:75], v[164:167], v[204:207], v[72:75]
	v_mfma_f32_16x16x32_bf16 v[60:63], v[156:159], v[212:215], v[60:63]
	v_mfma_f32_16x16x32_bf16 v[56:59], v[164:167], v[212:215], v[56:59]
	v_mfma_f32_16x16x32_bf16 v[28:31], v[168:171], v[184:187], v[28:31]
	v_mfma_f32_16x16x32_bf16 v[24:27], v[176:179], v[184:187], v[24:27]
	v_mfma_f32_16x16x32_bf16 v[20:23], v[168:171], v[192:195], v[20:23]
	v_mfma_f32_16x16x32_bf16 v[16:19], v[176:179], v[192:195], v[16:19]
	v_mfma_f32_16x16x32_bf16 v[12:15], v[168:171], v[200:203], v[12:15]
	v_mfma_f32_16x16x32_bf16 v[8:11], v[176:179], v[200:203], v[8:11]
	v_mfma_f32_16x16x32_bf16 v[4:7], v[168:171], v[208:211], v[4:7]
	v_mfma_f32_16x16x32_bf16 v[0:3], v[176:179], v[208:211], v[0:3]
	v_mfma_f32_16x16x32_bf16 v[28:31], v[172:175], v[188:191], v[28:31]
	v_mfma_f32_16x16x32_bf16 v[24:27], v[180:183], v[188:191], v[24:27]
	v_mfma_f32_16x16x32_bf16 v[20:23], v[172:175], v[196:199], v[20:23]
	v_mfma_f32_16x16x32_bf16 v[16:19], v[180:183], v[196:199], v[16:19]
	v_mfma_f32_16x16x32_bf16 v[12:15], v[172:175], v[204:207], v[12:15]
	v_mfma_f32_16x16x32_bf16 v[8:11], v[180:183], v[204:207], v[8:11]
	v_mfma_f32_16x16x32_bf16 v[4:7], v[172:175], v[212:215], v[4:7]
	v_mfma_f32_16x16x32_bf16 v[0:3], v[180:183], v[212:215], v[0:3]
	s_barrier
	s_add_i32 s45, s45, 2
	s_add_u32 s43, s43, 0x100
	s_addc_u32 s44, s44, 0
	s_cmpk_gt_u32 s45, 0x55
	s_mov_b64 s[20:21], s[26:27]
	s_cbranch_scc0 .LBB0_1810
	s_and_b64 vcc, exec, s[22:23]
	s_cbranch_vccz .LBB0_1813
	s_barrier
